# P2 deferred weight/p conversions: non-temporal loads and stores (streamed once, consumed much later), on top of nt GL/GA/V^T stores
# speedup vs baseline: 1.0190x; 1.0132x over previous
; template <bool F8 = false>
; __device__ __forceinline__ void p0_transpose_item(const float* W, int K, int N, bf16_t* WT, int k0, int n0, int drow0, const float* gs, LAS float* scr, int lane) {
;     ...
;     for (int i = 0; i < 32; ++i) wv[i] = W[(size_t)(k0 + 2 * i + (lane >> 5)) * N + n0 + (lane & 31)];
;     if (gs) {
; #pragma unroll
;         for (int i = 0; i < 32; ++i) wv[i] *= gs[k0 + 2 * i + (lane >> 5)]; }
; #pragma unroll
;     for (int i = 0; i < 32; ++i) scr[(2 * i + (lane >> 5)) * 33 + (lane & 31)] = wv[i];
; template <int PART>
; __device__ __forceinline__ void phase0(const Ptrs& P, LAS float* scr, int gw, int NGW, int lane) {
;     ...
;         { const int nblk = DM / 32; p0_transpose_item(P.w_ple, PLE, DM, (bf16_t*)(ws + WS_WPLE), 64 * (r / nblk), 32 * (r % nblk), 32 * (r % nblk), nullptr, scr, lane); }
.LBB0_413:
	s_cmp_gt_i32 s24, -1
	s_mov_b64 s[0:1], -1
	s_cbranch_scc0 .LBB0_443
	s_cmpk_gt_u32 s24, 0x1ff
	s_cbranch_scc0 .LBB0_440
	s_cmpk_gt_u32 s24, 0x3ff
	s_cbranch_scc0 .LBB0_437
	s_cmpk_gt_u32 s24, 0x5ff
	s_cbranch_scc0 .LBB0_434
	s_cmpk_gt_u32 s24, 0x7ff
	s_cbranch_scc0 .LBB0_429
	s_cmpk_gt_u32 s24, 0xfff
	s_cbranch_scc0 .LBB0_424
	s_and_b32 s2, s8, 0x3e0
	s_cmpk_gt_u32 s24, 0x17ff
	v_add_u32_e32 v40, s2, v75
	v_add_u32_e32 v38, s2, v77
	v_add_u32_e32 v36, s2, v78
	v_add_u32_e32 v34, s2, v79
	s_cbranch_scc0 .LBB0_421
	s_and_b32 s0, s9, 0x7fffffc0
	v_add_u32_e32 v42, s0, v70
	s_lshl_b32 s68, s2, 2
	v_ashrrev_i32_e32 v43, 31, v42
	v_lshl_add_u64 v[44:45], v[18:19], 0, s[68:69]
	v_lshlrev_b64 v[42:43], 12, v[42:43]
	v_lshl_add_u64 v[42:43], v[44:45], 0, v[42:43]
	v_add_co_u32_e32 v44, vcc, 0x2000, v42
	global_load_dword v35, v[42:43], off nt
	s_nop 0
	v_addc_co_u32_e32 v45, vcc, 0, v43, vcc
	global_load_dword v37, v[44:45], off nt
	v_add_co_u32_e32 v44, vcc, 0x4000, v42
	s_lshl_b32 s68, s0, 1
	s_nop 0
	v_addc_co_u32_e32 v45, vcc, 0, v43, vcc
	global_load_dword v39, v[44:45], off nt
	v_add_co_u32_e32 v44, vcc, 0x6000, v42
	s_mov_b64 s[0:1], 0
	s_nop 0
	v_addc_co_u32_e32 v45, vcc, 0, v43, vcc
	global_load_dword v41, v[44:45], off nt
	v_add_co_u32_e32 v44, vcc, 0x8000, v42
	s_nop 1
	v_addc_co_u32_e32 v45, vcc, 0, v43, vcc
	global_load_dword v46, v[44:45], off nt
	v_add_co_u32_e32 v44, vcc, 0xa000, v42
	s_nop 1
	v_addc_co_u32_e32 v45, vcc, 0, v43, vcc
	global_load_dword v47, v[44:45], off nt
	v_add_co_u32_e32 v44, vcc, 0xc000, v42
	s_nop 1
	v_addc_co_u32_e32 v45, vcc, 0, v43, vcc
	global_load_dword v48, v[44:45], off nt
	v_add_co_u32_e32 v44, vcc, 0xe000, v42
	s_nop 1
	v_addc_co_u32_e32 v45, vcc, 0, v43, vcc
	global_load_dword v49, v[44:45], off nt
	v_add_co_u32_e32 v44, vcc, 0x10000, v42
	s_nop 1
	v_addc_co_u32_e32 v45, vcc, 0, v43, vcc
	global_load_dword v50, v[44:45], off nt
	v_add_co_u32_e32 v44, vcc, 0x12000, v42
	s_nop 1
	v_addc_co_u32_e32 v45, vcc, 0, v43, vcc
	global_load_dword v51, v[44:45], off nt
	v_add_co_u32_e32 v44, vcc, 0x14000, v42
	s_nop 1
	v_addc_co_u32_e32 v45, vcc, 0, v43, vcc
	global_load_dword v52, v[44:45], off nt
	v_add_co_u32_e32 v44, vcc, 0x16000, v42
	s_nop 1
	v_addc_co_u32_e32 v45, vcc, 0, v43, vcc
	global_load_dword v53, v[44:45], off nt
	v_add_co_u32_e32 v44, vcc, 0x18000, v42
	s_nop 1
	v_addc_co_u32_e32 v45, vcc, 0, v43, vcc
	global_load_dword v54, v[44:45], off nt
	v_add_co_u32_e32 v44, vcc, 0x1a000, v42
	s_nop 1
	v_addc_co_u32_e32 v45, vcc, 0, v43, vcc
	global_load_dword v55, v[44:45], off nt
	v_add_co_u32_e32 v44, vcc, 0x1c000, v42
	s_nop 1
	v_addc_co_u32_e32 v45, vcc, 0, v43, vcc
	global_load_dword v56, v[44:45], off nt
	v_add_co_u32_e32 v44, vcc, 0x1e000, v42
	s_nop 1
	v_addc_co_u32_e32 v45, vcc, 0, v43, vcc
	global_load_dword v57, v[44:45], off nt
	v_add_co_u32_e32 v44, vcc, 0x20000, v42
	s_nop 1
	v_addc_co_u32_e32 v45, vcc, 0, v43, vcc
	global_load_dword v58, v[44:45], off nt
	v_add_co_u32_e32 v44, vcc, 0x22000, v42
	s_nop 1
	v_addc_co_u32_e32 v45, vcc, 0, v43, vcc
	global_load_dword v59, v[44:45], off nt
	v_add_co_u32_e32 v44, vcc, 0x24000, v42
	s_nop 1
	v_addc_co_u32_e32 v45, vcc, 0, v43, vcc
	global_load_dword v60, v[44:45], off nt
	v_add_co_u32_e32 v44, vcc, 0x26000, v42
	s_nop 1
	v_addc_co_u32_e32 v45, vcc, 0, v43, vcc
	global_load_dword v61, v[44:45], off nt
	v_add_co_u32_e32 v44, vcc, 0x28000, v42
	s_nop 1
	v_addc_co_u32_e32 v45, vcc, 0, v43, vcc
	global_load_dword v62, v[44:45], off nt
	v_add_co_u32_e32 v44, vcc, 0x2a000, v42
	s_nop 1
	v_addc_co_u32_e32 v45, vcc, 0, v43, vcc
	global_load_dword v63, v[44:45], off nt
	v_add_co_u32_e32 v44, vcc, 0x2c000, v42
	s_nop 1
	v_addc_co_u32_e32 v45, vcc, 0, v43, vcc
	global_load_dword v64, v[44:45], off nt
	v_add_co_u32_e32 v44, vcc, 0x2e000, v42
	s_nop 1
	v_addc_co_u32_e32 v45, vcc, 0, v43, vcc
	global_load_dword v65, v[44:45], off nt
	v_add_co_u32_e32 v44, vcc, 0x30000, v42
	s_nop 1
	v_addc_co_u32_e32 v45, vcc, 0, v43, vcc
	global_load_dword v66, v[44:45], off nt
	v_add_co_u32_e32 v44, vcc, 0x32000, v42
	s_nop 1
	v_addc_co_u32_e32 v45, vcc, 0, v43, vcc
	global_load_dword v67, v[44:45], off nt
	v_add_co_u32_e32 v44, vcc, 0x34000, v42
	s_nop 1
	v_addc_co_u32_e32 v45, vcc, 0, v43, vcc
	global_load_dword v68, v[44:45], off nt
	v_add_co_u32_e32 v44, vcc, 0x36000, v42
	s_nop 1
	v_addc_co_u32_e32 v45, vcc, 0, v43, vcc
	global_load_dword v69, v[44:45], off nt
	v_add_co_u32_e32 v44, vcc, 0x38000, v42
	s_nop 1
	v_addc_co_u32_e32 v45, vcc, 0, v43, vcc
	global_load_dword v86, v[44:45], off nt
	v_add_co_u32_e32 v44, vcc, 0x3a000, v42
	s_nop 1
	v_addc_co_u32_e32 v45, vcc, 0, v43, vcc
	global_load_dword v87, v[44:45], off nt
	v_add_co_u32_e32 v44, vcc, 0x3c000, v42
	s_nop 1
	v_addc_co_u32_e32 v45, vcc, 0, v43, vcc
	v_add_co_u32_e32 v42, vcc, 0x3e000, v42
	global_load_dword v44, v[44:45], off nt
	s_nop 0
	v_addc_co_u32_e32 v43, vcc, 0, v43, vcc
	global_load_dword v42, v[42:43], off nt
	s_waitcnt vmcnt(0)
	ds_write2_b32 v71, v35, v37 offset1:66
	ds_write2_b32 v71, v39, v41 offset0:132 offset1:198
	ds_write2_b32 v72, v46, v47 offset0:8 offset1:74
	ds_write2_b32 v72, v48, v49 offset0:140 offset1:206
	ds_write2_b32 v80, v50, v51 offset0:16 offset1:82
	ds_write2_b32 v80, v52, v53 offset0:148 offset1:214
	ds_write2_b32 v82, v54, v55 offset0:24 offset1:90
	ds_write2_b32 v82, v56, v57 offset0:156 offset1:222
	ds_write2_b32 v83, v58, v59 offset0:32 offset1:98
	ds_write2_b32 v83, v60, v61 offset0:164 offset1:230
	ds_write2_b32 v84, v62, v63 offset0:40 offset1:106
	ds_write2_b32 v84, v64, v65 offset0:172 offset1:238
	ds_write2_b32 v85, v66, v67 offset0:48 offset1:114
	ds_write2_b32 v85, v68, v69 offset0:180 offset1:246
	v_add_u32_e32 v35, 0x1c00, v71
	ds_write2_b32 v35, v86, v87 offset0:56 offset1:122
	ds_write2_b32 v35, v44, v42 offset0:188 offset1:254
	s_waitcnt lgkmcnt(0)
; #define LAS __attribute__((address_space(3)))
; __device__ __forceinline__ unsigned cvt_pk(float lo, float hi) { f32x2_t v = {lo, hi}; bf16x2_t b = __builtin_convertvector(v, bf16x2_t); return __builtin_bit_cast(unsigned, b); }
; __device__ __forceinline__ unsigned pk_fp8x4(float a, float b, float c, float d) { int w = 0; w = __builtin_amdgcn_cvt_pk_fp8_f32(a, b, w, false); w = __builtin_amdgcn_cvt_pk_fp8_f32(c, d, w, true); return (unsigned)w; }
; template <bool F8 = false>
; __device__ __forceinline__ void p0_transpose_item(const float* W, int K, int N, bf16_t* WT, int k0, int n0, int drow0, const float* gs, LAS float* scr, int lane) {
;     ...
;     for (int i = 0; i < 32; ++i) wv[i] = W[(size_t)(k0 + 2 * i + (lane >> 5)) * N + n0 + (lane & 31)];
;     ...
;     const int c = lane & 7;
; #pragma unroll
;     for (int j = 0; j < 4; ++j) { const int n = (lane >> 3) + 8 * j; const LAS float* s = scr + (8 * c) * 33 + n;
;         if (F8) { u32x2 o8; o8.x = pk_fp8x4(32.f * s[0 * 33], 32.f * s[1 * 33], 32.f * s[2 * 33], 32.f * s[3 * 33]); o8.y = pk_fp8x4(32.f * s[4 * 33], 32.f * s[5 * 33], 32.f * s[6 * 33], 32.f * s[7 * 33]);
;             *(u32x2*)((unsigned char*)WT + (size_t)(drow0 + n) * K + k0 + 8 * c) = o8; }
;         else { u32x4 o; o.x = cvt_pk(s[0 * 33], s[1 * 33]); o.y = cvt_pk(s[2 * 33], s[3 * 33]); o.z = cvt_pk(s[4 * 33], s[5 * 33]); o.w = cvt_pk(s[6 * 33], s[7 * 33]);
;             *(u32x4*)(WT + (size_t)(drow0 + n) * K + k0 + 8 * c) = o; } }
; template <int PART>
; __device__ __forceinline__ void phase0(const Ptrs& P, LAS float* scr, int gw, int NGW, int lane) {
;     ...
;         if (r < I_DN) { const int nblk = DM / 32; p0_transpose_item(P.w_dn, FF, DM, (bf16_t*)(ws + WS_WDN), 64 * (r / nblk), 32 * (r % nblk), 32 * (r % nblk), nullptr, scr, lane); continue; } r -= I_DN;
	ds_read2_b32 v[48:49], v76 offset0:33 offset1:41
	ds_read2_b32 v[50:51], v76 offset1:8
	ds_read2_b32 v[52:53], v76 offset0:66 offset1:74
	ds_read2_b32 v[54:55], v76 offset0:99 offset1:107
	ds_read2_b32 v[56:57], v76 offset0:132 offset1:140
	ds_read2_b32 v[58:59], v76 offset0:165 offset1:173
	ds_read2_b32 v[60:61], v76 offset0:198 offset1:206
	ds_read2_b32 v[62:63], v76 offset0:231 offset1:239
	v_ashrrev_i32_e32 v41, 31, v40
	v_lshl_add_u64 v[46:47], v[0:1], 0, s[68:69]
	v_lshlrev_b64 v[64:65], 9, v[40:41]
	s_waitcnt lgkmcnt(6)
	v_cvt_pk_bf16_f32 v42, v50, v48
	s_waitcnt lgkmcnt(4)
	v_cvt_pk_bf16_f32 v43, v52, v54
	s_waitcnt lgkmcnt(2)
	v_cvt_pk_bf16_f32 v44, v56, v58
	s_waitcnt lgkmcnt(0)
	v_cvt_pk_bf16_f32 v45, v60, v62
	v_lshl_add_u64 v[64:65], v[46:47], 0, v[64:65]
	v_ashrrev_i32_e32 v39, 31, v38
	global_store_dwordx4 v[64:65], v[42:45], off nt
	v_ashrrev_i32_e32 v37, 31, v36
	v_lshlrev_b64 v[64:65], 9, v[36:37]
	v_cvt_pk_bf16_f32 v42, v51, v49
	v_lshlrev_b64 v[48:49], 9, v[38:39]
	v_cvt_pk_bf16_f32 v43, v53, v55
	v_cvt_pk_bf16_f32 v44, v57, v59
	v_cvt_pk_bf16_f32 v45, v61, v63
	v_lshl_add_u64 v[48:49], v[46:47], 0, v[48:49]
	global_store_dwordx4 v[48:49], v[42:45], off nt
	ds_read2_b32 v[48:49], v76 offset0:16 offset1:24
	ds_read2_b32 v[50:51], v76 offset0:49 offset1:57
	ds_read2_b32 v[52:53], v76 offset0:82 offset1:90
	ds_read2_b32 v[54:55], v76 offset0:115 offset1:123
	ds_read2_b32 v[56:57], v76 offset0:148 offset1:156
	ds_read2_b32 v[58:59], v76 offset0:181 offset1:189
	ds_read2_b32 v[60:61], v76 offset0:214 offset1:222
	ds_read2_b32 v[62:63], v76 offset0:247 offset1:255
	v_lshl_add_u64 v[64:65], v[46:47], 0, v[64:65]
	s_waitcnt lgkmcnt(6)
	v_cvt_pk_bf16_f32 v42, v48, v50
	s_waitcnt lgkmcnt(4)
	v_cvt_pk_bf16_f32 v43, v52, v54
	s_waitcnt lgkmcnt(2)
	v_cvt_pk_bf16_f32 v44, v56, v58
	s_waitcnt lgkmcnt(0)
	v_cvt_pk_bf16_f32 v45, v60, v62
	v_ashrrev_i32_e32 v35, 31, v34
	global_store_dwordx4 v[64:65], v[42:45], off nt
	s_nop 1
	v_cvt_pk_bf16_f32 v42, v49, v51
	v_lshlrev_b64 v[48:49], 9, v[34:35]
	v_cvt_pk_bf16_f32 v43, v53, v55
	v_cvt_pk_bf16_f32 v44, v57, v59
	v_cvt_pk_bf16_f32 v45, v61, v63
	v_lshl_add_u64 v[46:47], v[46:47], 0, v[48:49]
	global_store_dwordx4 v[46:47], v[42:45], off nt
	s_waitcnt lgkmcnt(0)
.LBB0_421:
	s_andn2_b64 vcc, exec, s[0:1]
	s_cbranch_vccnz .LBB0_423
	s_add_i32 s0, s9, 0x1000
	s_and_b32 s0, s0, 0x7fffffc0
	v_add_u32_e32 v42, s0, v70
	s_lshl_b32 s68, s2, 2
	v_ashrrev_i32_e32 v43, 31, v42
	v_lshl_add_u64 v[44:45], v[20:21], 0, s[68:69]
	v_lshlrev_b64 v[42:43], 12, v[42:43]
	v_lshl_add_u64 v[42:43], v[44:45], 0, v[42:43]
	v_add_co_u32_e32 v44, vcc, 0x2000, v42
	global_load_dword v35, v[42:43], off nt
	s_nop 0
	v_addc_co_u32_e32 v45, vcc, 0, v43, vcc
	global_load_dword v37, v[44:45], off nt
	v_add_co_u32_e32 v44, vcc, 0x4000, v42
	s_lshl_b32 s68, s0, 1
	s_nop 0
	v_addc_co_u32_e32 v45, vcc, 0, v43, vcc
	global_load_dword v39, v[44:45], off nt
	v_add_co_u32_e32 v44, vcc, 0x6000, v42
	s_nop 1
	v_addc_co_u32_e32 v45, vcc, 0, v43, vcc
	global_load_dword v41, v[44:45], off nt
	v_add_co_u32_e32 v44, vcc, 0x8000, v42
	s_nop 1
	v_addc_co_u32_e32 v45, vcc, 0, v43, vcc
	global_load_dword v46, v[44:45], off nt
	v_add_co_u32_e32 v44, vcc, 0xa000, v42
	s_nop 1
	v_addc_co_u32_e32 v45, vcc, 0, v43, vcc
	global_load_dword v47, v[44:45], off nt
	v_add_co_u32_e32 v44, vcc, 0xc000, v42
	s_nop 1
	v_addc_co_u32_e32 v45, vcc, 0, v43, vcc
	global_load_dword v48, v[44:45], off nt
	v_add_co_u32_e32 v44, vcc, 0xe000, v42
	s_nop 1
	v_addc_co_u32_e32 v45, vcc, 0, v43, vcc
	global_load_dword v49, v[44:45], off nt
	v_add_co_u32_e32 v44, vcc, 0x10000, v42
	s_nop 1
	v_addc_co_u32_e32 v45, vcc, 0, v43, vcc
	global_load_dword v50, v[44:45], off nt
	v_add_co_u32_e32 v44, vcc, 0x12000, v42
	s_nop 1
	v_addc_co_u32_e32 v45, vcc, 0, v43, vcc
	global_load_dword v51, v[44:45], off nt
	v_add_co_u32_e32 v44, vcc, 0x14000, v42
	s_nop 1
	v_addc_co_u32_e32 v45, vcc, 0, v43, vcc
	global_load_dword v52, v[44:45], off nt
	v_add_co_u32_e32 v44, vcc, 0x16000, v42
	s_nop 1
	v_addc_co_u32_e32 v45, vcc, 0, v43, vcc
	global_load_dword v53, v[44:45], off nt
	v_add_co_u32_e32 v44, vcc, 0x18000, v42
	s_nop 1
	v_addc_co_u32_e32 v45, vcc, 0, v43, vcc
	global_load_dword v54, v[44:45], off nt
	v_add_co_u32_e32 v44, vcc, 0x1a000, v42
	s_nop 1
	v_addc_co_u32_e32 v45, vcc, 0, v43, vcc
	global_load_dword v55, v[44:45], off nt
	v_add_co_u32_e32 v44, vcc, 0x1c000, v42
	s_nop 1
	v_addc_co_u32_e32 v45, vcc, 0, v43, vcc
	global_load_dword v56, v[44:45], off nt
	v_add_co_u32_e32 v44, vcc, 0x1e000, v42
	s_nop 1
	v_addc_co_u32_e32 v45, vcc, 0, v43, vcc
	global_load_dword v57, v[44:45], off nt
	v_add_co_u32_e32 v44, vcc, 0x20000, v42
	s_nop 1
	v_addc_co_u32_e32 v45, vcc, 0, v43, vcc
	global_load_dword v58, v[44:45], off nt
	v_add_co_u32_e32 v44, vcc, 0x22000, v42
	s_nop 1
	v_addc_co_u32_e32 v45, vcc, 0, v43, vcc
	global_load_dword v59, v[44:45], off nt
	v_add_co_u32_e32 v44, vcc, 0x24000, v42
	s_nop 1
	v_addc_co_u32_e32 v45, vcc, 0, v43, vcc
	global_load_dword v60, v[44:45], off nt
	v_add_co_u32_e32 v44, vcc, 0x26000, v42
	s_nop 1
	v_addc_co_u32_e32 v45, vcc, 0, v43, vcc
	global_load_dword v61, v[44:45], off nt
	v_add_co_u32_e32 v44, vcc, 0x28000, v42
	s_nop 1
	v_addc_co_u32_e32 v45, vcc, 0, v43, vcc
	global_load_dword v62, v[44:45], off nt
	v_add_co_u32_e32 v44, vcc, 0x2a000, v42
	s_nop 1
	v_addc_co_u32_e32 v45, vcc, 0, v43, vcc
	global_load_dword v63, v[44:45], off nt
	v_add_co_u32_e32 v44, vcc, 0x2c000, v42
	s_nop 1
	v_addc_co_u32_e32 v45, vcc, 0, v43, vcc
	global_load_dword v64, v[44:45], off nt
	v_add_co_u32_e32 v44, vcc, 0x2e000, v42
	s_nop 1
	v_addc_co_u32_e32 v45, vcc, 0, v43, vcc
	global_load_dword v65, v[44:45], off nt
	v_add_co_u32_e32 v44, vcc, 0x30000, v42
	s_nop 1
	v_addc_co_u32_e32 v45, vcc, 0, v43, vcc
	global_load_dword v66, v[44:45], off nt
	v_add_co_u32_e32 v44, vcc, 0x32000, v42
	s_nop 1
	v_addc_co_u32_e32 v45, vcc, 0, v43, vcc
	global_load_dword v67, v[44:45], off nt
	v_add_co_u32_e32 v44, vcc, 0x34000, v42
	s_nop 1
	v_addc_co_u32_e32 v45, vcc, 0, v43, vcc
	global_load_dword v68, v[44:45], off nt
	v_add_co_u32_e32 v44, vcc, 0x36000, v42
	s_nop 1
	v_addc_co_u32_e32 v45, vcc, 0, v43, vcc
	global_load_dword v69, v[44:45], off nt
	v_add_co_u32_e32 v44, vcc, 0x38000, v42
	s_nop 1
	v_addc_co_u32_e32 v45, vcc, 0, v43, vcc
	global_load_dword v86, v[44:45], off nt
	v_add_co_u32_e32 v44, vcc, 0x3a000, v42
	s_nop 1
	v_addc_co_u32_e32 v45, vcc, 0, v43, vcc
	global_load_dword v87, v[44:45], off nt
	v_add_co_u32_e32 v44, vcc, 0x3c000, v42
	s_nop 1
	v_addc_co_u32_e32 v45, vcc, 0, v43, vcc
	v_add_co_u32_e32 v42, vcc, 0x3e000, v42
	global_load_dword v44, v[44:45], off nt
	s_nop 0
	v_addc_co_u32_e32 v43, vcc, 0, v43, vcc
	global_load_dword v42, v[42:43], off nt
	s_waitcnt vmcnt(0)
; #define LAS __attribute__((address_space(3)))
; __device__ __forceinline__ unsigned cvt_pk(float lo, float hi) { f32x2_t v = {lo, hi}; bf16x2_t b = __builtin_convertvector(v, bf16x2_t); return __builtin_bit_cast(unsigned, b); }
; __device__ __forceinline__ unsigned pk_fp8x4(float a, float b, float c, float d) { int w = 0; w = __builtin_amdgcn_cvt_pk_fp8_f32(a, b, w, false); w = __builtin_amdgcn_cvt_pk_fp8_f32(c, d, w, true); return (unsigned)w; }
; template <bool F8 = false>
; __device__ __forceinline__ void p0_transpose_item(const float* W, int K, int N, bf16_t* WT, int k0, int n0, int drow0, const float* gs, LAS float* scr, int lane) {
;     ...
;     for (int i = 0; i < 32; ++i) scr[(2 * i + (lane >> 5)) * 33 + (lane & 31)] = wv[i];
;     asm volatile("s_waitcnt lgkmcnt(0)" ::: "memory");
;     const int c = lane & 7;
; #pragma unroll
;     for (int j = 0; j < 4; ++j) { const int n = (lane >> 3) + 8 * j; const LAS float* s = scr + (8 * c) * 33 + n;
;         if (F8) { u32x2 o8; o8.x = pk_fp8x4(32.f * s[0 * 33], 32.f * s[1 * 33], 32.f * s[2 * 33], 32.f * s[3 * 33]); o8.y = pk_fp8x4(32.f * s[4 * 33], 32.f * s[5 * 33], 32.f * s[6 * 33], 32.f * s[7 * 33]);
;             *(u32x2*)((unsigned char*)WT + (size_t)(drow0 + n) * K + k0 + 8 * c) = o8; }
;         else { u32x4 o; o.x = cvt_pk(s[0 * 33], s[1 * 33]); o.y = cvt_pk(s[2 * 33], s[3 * 33]); o.z = cvt_pk(s[4 * 33], s[5 * 33]); o.w = cvt_pk(s[6 * 33], s[7 * 33]);
;             *(u32x4*)(WT + (size_t)(drow0 + n) * K + k0 + 8 * c) = o; } }
	ds_write2_b32 v71, v35, v37 offset1:66
	ds_write2_b32 v71, v39, v41 offset0:132 offset1:198
	ds_write2_b32 v72, v46, v47 offset0:8 offset1:74
	ds_write2_b32 v72, v48, v49 offset0:140 offset1:206
	ds_write2_b32 v80, v50, v51 offset0:16 offset1:82
	ds_write2_b32 v80, v52, v53 offset0:148 offset1:214
	ds_write2_b32 v82, v54, v55 offset0:24 offset1:90
	ds_write2_b32 v82, v56, v57 offset0:156 offset1:222
	ds_write2_b32 v83, v58, v59 offset0:32 offset1:98
	ds_write2_b32 v83, v60, v61 offset0:164 offset1:230
	ds_write2_b32 v84, v62, v63 offset0:40 offset1:106
	ds_write2_b32 v84, v64, v65 offset0:172 offset1:238
	ds_write2_b32 v85, v66, v67 offset0:48 offset1:114
	ds_write2_b32 v85, v68, v69 offset0:180 offset1:246
	v_add_u32_e32 v35, 0x1c00, v71
	ds_write2_b32 v35, v86, v87 offset0:56 offset1:122
	ds_write2_b32 v35, v44, v42 offset0:188 offset1:254
	s_waitcnt lgkmcnt(0)
	ds_read2_b32 v[48:49], v76 offset0:33 offset1:41
	ds_read2_b32 v[50:51], v76 offset1:8
	ds_read2_b32 v[52:53], v76 offset0:66 offset1:74
	ds_read2_b32 v[54:55], v76 offset0:99 offset1:107
	ds_read2_b32 v[56:57], v76 offset0:132 offset1:140
	ds_read2_b32 v[58:59], v76 offset0:165 offset1:173
	ds_read2_b32 v[60:61], v76 offset0:198 offset1:206
	ds_read2_b32 v[62:63], v76 offset0:231 offset1:239
	v_ashrrev_i32_e32 v41, 31, v40
	v_lshl_add_u64 v[46:47], v[2:3], 0, s[68:69]
	v_lshlrev_b64 v[40:41], 13, v[40:41]
	v_ashrrev_i32_e32 v39, 31, v38
	s_waitcnt lgkmcnt(6)
	v_cvt_pk_bf16_f32 v42, v50, v48
	s_waitcnt lgkmcnt(4)
	v_cvt_pk_bf16_f32 v43, v52, v54
	s_waitcnt lgkmcnt(2)
	v_cvt_pk_bf16_f32 v44, v56, v58
	s_waitcnt lgkmcnt(0)
	v_cvt_pk_bf16_f32 v45, v60, v62
	v_lshl_add_u64 v[40:41], v[46:47], 0, v[40:41]
	v_lshlrev_b64 v[38:39], 13, v[38:39]
	global_store_dwordx4 v[40:41], v[42:45], off nt
	v_cvt_pk_bf16_f32 v40, v51, v49
	v_cvt_pk_bf16_f32 v41, v53, v55
	v_cvt_pk_bf16_f32 v42, v57, v59
	v_cvt_pk_bf16_f32 v43, v61, v63
	v_lshl_add_u64 v[38:39], v[46:47], 0, v[38:39]
	global_store_dwordx4 v[38:39], v[40:43], off nt
	ds_read2_b32 v[42:43], v76 offset0:16 offset1:24
	ds_read2_b32 v[44:45], v76 offset0:49 offset1:57
	ds_read2_b32 v[48:49], v76 offset0:82 offset1:90
	ds_read2_b32 v[50:51], v76 offset0:115 offset1:123
	ds_read2_b32 v[52:53], v76 offset0:148 offset1:156
	ds_read2_b32 v[54:55], v76 offset0:181 offset1:189
	ds_read2_b32 v[56:57], v76 offset0:214 offset1:222
	ds_read2_b32 v[58:59], v76 offset0:247 offset1:255
	v_ashrrev_i32_e32 v37, 31, v36
	v_lshlrev_b64 v[36:37], 13, v[36:37]
	v_ashrrev_i32_e32 v35, 31, v34
	s_waitcnt lgkmcnt(6)
	v_cvt_pk_bf16_f32 v38, v42, v44
	s_waitcnt lgkmcnt(4)
	v_cvt_pk_bf16_f32 v39, v48, v50
	s_waitcnt lgkmcnt(2)
	v_cvt_pk_bf16_f32 v40, v52, v54
	s_waitcnt lgkmcnt(0)
	v_cvt_pk_bf16_f32 v41, v56, v58
	v_lshl_add_u64 v[36:37], v[46:47], 0, v[36:37]
	v_lshlrev_b64 v[34:35], 13, v[34:35]
	global_store_dwordx4 v[36:37], v[38:41], off nt
	v_cvt_pk_bf16_f32 v36, v43, v45
	v_cvt_pk_bf16_f32 v37, v49, v51
	v_cvt_pk_bf16_f32 v38, v53, v55
	v_cvt_pk_bf16_f32 v39, v57, v59
	v_lshl_add_u64 v[34:35], v[46:47], 0, v[34:35]
	global_store_dwordx4 v[34:35], v[36:39], off nt
	s_waitcnt lgkmcnt(0)

; template <bool F8 = false>
; __device__ __forceinline__ void p0_transpose_item(const float* W, int K, int N, bf16_t* WT, int k0, int n0, int drow0, const float* gs, LAS float* scr, int lane) {
;     ...
;     for (int i = 0; i < 32; ++i) wv[i] = W[(size_t)(k0 + 2 * i + (lane >> 5)) * N + n0 + (lane & 31)];
;     if (gs) {
; #pragma unroll
;         for (int i = 0; i < 32; ++i) wv[i] *= gs[k0 + 2 * i + (lane >> 5)]; }
; template <int PART>
; __device__ __forceinline__ void phase0(const Ptrs& P, LAS float* scr, int gw, int NGW, int lane) {
;     ...
;         if (r < I_UP) { const int nblk = FF / 32; p0_transpose_item(P.w_up, DM, FF, (bf16_t*)(ws + WS_WUP), 64 * (r / nblk), 32 * (r % nblk), 32 * (r % nblk), P.g_mlp, scr, lane); continue; } r -= I_UP;
.LBB0_424:
	s_andn2_b64 vcc, exec, s[0:1]
	s_cbranch_vccnz .LBB0_428
	s_add_i32 s0, s24, 0xfffff800
	s_lshr_b32 s0, s0, 1
	s_and_b32 s1, s0, 0x7fffffc0
	s_and_b32 s0, s8, 0xfe0
	v_add_u32_e32 v56, s1, v70
	s_lshl_b32 s68, s0, 2
	v_ashrrev_i32_e32 v57, 31, v56
	v_lshl_add_u64 v[34:35], v[22:23], 0, s[68:69]
	v_lshlrev_b64 v[36:37], 14, v[56:57]
	v_lshl_add_u64 v[60:61], v[34:35], 0, v[36:37]
	v_add_co_u32_e32 v36, vcc, 0x8000, v60
	global_load_dword v34, v[60:61], off nt
	s_nop 0
	v_addc_co_u32_e32 v37, vcc, 0, v61, vcc
	global_load_dword v35, v[36:37], off nt
	v_add_co_u32_e32 v36, vcc, 0x10000, v60
	v_readlane_b32 s2, v246, 8
	s_nop 0
	v_addc_co_u32_e32 v37, vcc, 0, v61, vcc
	v_add_co_u32_e32 v38, vcc, 0x18000, v60
	global_load_dword v36, v[36:37], off nt
	s_nop 0
	v_addc_co_u32_e32 v39, vcc, 0, v61, vcc
	global_load_dword v37, v[38:39], off nt
	v_add_co_u32_e32 v38, vcc, 0x20000, v60
	v_readlane_b32 s3, v246, 9
	s_nop 0
	v_addc_co_u32_e32 v39, vcc, 0, v61, vcc
	v_add_co_u32_e32 v40, vcc, 0x28000, v60
	global_load_dword v38, v[38:39], off nt
	s_nop 0
	v_addc_co_u32_e32 v41, vcc, 0, v61, vcc
	global_load_dword v39, v[40:41], off nt
	v_add_co_u32_e32 v40, vcc, 0x30000, v60
	s_nop 1
	v_addc_co_u32_e32 v41, vcc, 0, v61, vcc
	v_add_co_u32_e32 v42, vcc, 0x38000, v60
	global_load_dword v40, v[40:41], off nt
	s_nop 0
	v_addc_co_u32_e32 v43, vcc, 0, v61, vcc
	global_load_dword v41, v[42:43], off nt
	v_add_co_u32_e32 v42, vcc, 0x40000, v60
	s_nop 1
	v_addc_co_u32_e32 v43, vcc, 0, v61, vcc
	v_add_co_u32_e32 v44, vcc, 0x48000, v60
	global_load_dword v42, v[42:43], off nt
	s_nop 0
	v_addc_co_u32_e32 v45, vcc, 0, v61, vcc
	global_load_dword v43, v[44:45], off nt
	v_add_co_u32_e32 v44, vcc, 0x50000, v60
	s_nop 1
	v_addc_co_u32_e32 v45, vcc, 0, v61, vcc
	v_add_co_u32_e32 v46, vcc, 0x58000, v60
	global_load_dword v44, v[44:45], off nt
	s_nop 0
	v_addc_co_u32_e32 v47, vcc, 0, v61, vcc
	global_load_dword v45, v[46:47], off nt
	v_add_co_u32_e32 v46, vcc, 0x60000, v60
	s_nop 1
	v_addc_co_u32_e32 v47, vcc, 0, v61, vcc
	v_add_co_u32_e32 v48, vcc, 0x68000, v60
	global_load_dword v46, v[46:47], off nt
	s_nop 0
	v_addc_co_u32_e32 v49, vcc, 0, v61, vcc
	global_load_dword v47, v[48:49], off nt
	v_add_co_u32_e32 v48, vcc, 0x70000, v60
	s_nop 1
	v_addc_co_u32_e32 v49, vcc, 0, v61, vcc
	v_add_co_u32_e32 v50, vcc, 0x78000, v60
	global_load_dword v48, v[48:49], off nt
	s_nop 0
	v_addc_co_u32_e32 v51, vcc, 0, v61, vcc
	global_load_dword v49, v[50:51], off nt
	v_add_co_u32_e32 v50, vcc, 0x80000, v60
	s_nop 1
	v_addc_co_u32_e32 v51, vcc, 0, v61, vcc
	v_add_co_u32_e32 v52, vcc, 0x88000, v60
	global_load_dword v50, v[50:51], off nt
	s_nop 0
	v_addc_co_u32_e32 v53, vcc, 0, v61, vcc
	global_load_dword v51, v[52:53], off nt
	v_add_co_u32_e32 v52, vcc, 0x90000, v60
	s_nop 1
	v_addc_co_u32_e32 v53, vcc, 0, v61, vcc
	v_add_co_u32_e32 v54, vcc, 0x98000, v60
	global_load_dword v52, v[52:53], off nt
	s_nop 0
	v_addc_co_u32_e32 v55, vcc, 0, v61, vcc
	global_load_dword v53, v[54:55], off nt
	v_add_co_u32_e32 v54, vcc, 0xa0000, v60
	s_nop 1
	v_addc_co_u32_e32 v55, vcc, 0, v61, vcc
	v_add_co_u32_e32 v58, vcc, 0xa8000, v60
	global_load_dword v54, v[54:55], off nt
	s_nop 0
	v_addc_co_u32_e32 v59, vcc, 0, v61, vcc
	global_load_dword v55, v[58:59], off nt
	v_add_co_u32_e32 v58, vcc, 0xb0000, v60
	s_nop 1
	v_addc_co_u32_e32 v59, vcc, 0, v61, vcc
	v_add_co_u32_e32 v62, vcc, 0xb8000, v60
	global_load_dword v58, v[58:59], off nt
	s_nop 0
	v_addc_co_u32_e32 v63, vcc, 0, v61, vcc
	global_load_dword v59, v[62:63], off nt
	v_add_co_u32_e32 v62, vcc, 0xc0000, v60
	s_nop 1
	v_addc_co_u32_e32 v63, vcc, 0, v61, vcc
	v_add_co_u32_e32 v64, vcc, 0xc8000, v60
	global_load_dword v62, v[62:63], off nt
	s_nop 0
	v_addc_co_u32_e32 v65, vcc, 0, v61, vcc
	global_load_dword v63, v[64:65], off nt
	v_add_co_u32_e32 v64, vcc, 0xd0000, v60
	s_nop 1
	v_addc_co_u32_e32 v65, vcc, 0, v61, vcc
	v_add_co_u32_e32 v66, vcc, 0xd8000, v60
	global_load_dword v64, v[64:65], off nt
	s_nop 0
	v_addc_co_u32_e32 v67, vcc, 0, v61, vcc
	global_load_dword v65, v[66:67], off nt
	v_add_co_u32_e32 v66, vcc, 0xe0000, v60
	s_nop 1
	v_addc_co_u32_e32 v67, vcc, 0, v61, vcc
	v_add_co_u32_e32 v68, vcc, 0xe8000, v60
	global_load_dword v66, v[66:67], off nt
	s_nop 0
	v_addc_co_u32_e32 v69, vcc, 0, v61, vcc
	global_load_dword v67, v[68:69], off nt
	v_add_co_u32_e32 v68, vcc, 0xf0000, v60
	s_nop 1
	v_addc_co_u32_e32 v69, vcc, 0, v61, vcc
	v_add_co_u32_e32 v60, vcc, 0xf8000, v60
	global_load_dword v68, v[68:69], off nt
	s_nop 0
	v_addc_co_u32_e32 v61, vcc, 0, v61, vcc
	global_load_dword v69, v[60:61], off nt
	s_andn2_b64 vcc, exec, s[2:3]
	s_cbranch_vccnz .LBB0_427
; #define LAS __attribute__((address_space(3)))
; __device__ __forceinline__ unsigned cvt_pk(float lo, float hi) { f32x2_t v = {lo, hi}; bf16x2_t b = __builtin_convertvector(v, bf16x2_t); return __builtin_bit_cast(unsigned, b); }
; __device__ __forceinline__ unsigned pk_fp8x4(float a, float b, float c, float d) { int w = 0; w = __builtin_amdgcn_cvt_pk_fp8_f32(a, b, w, false); w = __builtin_amdgcn_cvt_pk_fp8_f32(c, d, w, true); return (unsigned)w; }
; template <bool F8 = false>
; __device__ __forceinline__ void p0_transpose_item(const float* W, int K, int N, bf16_t* WT, int k0, int n0, int drow0, const float* gs, LAS float* scr, int lane) {
;     ...
;     if (gs) {
; #pragma unroll
;         for (int i = 0; i < 32; ++i) wv[i] *= gs[k0 + 2 * i + (lane >> 5)]; }
; #pragma unroll
;     for (int i = 0; i < 32; ++i) scr[(2 * i + (lane >> 5)) * 33 + (lane & 31)] = wv[i];
;     asm volatile("s_waitcnt lgkmcnt(0)" ::: "memory");
;     const int c = lane & 7;
; #pragma unroll
;     for (int j = 0; j < 4; ++j) { const int n = (lane >> 3) + 8 * j; const LAS float* s = scr + (8 * c) * 33 + n;
;         if (F8) { u32x2 o8; o8.x = pk_fp8x4(32.f * s[0 * 33], 32.f * s[1 * 33], 32.f * s[2 * 33], 32.f * s[3 * 33]); o8.y = pk_fp8x4(32.f * s[4 * 33], 32.f * s[5 * 33], 32.f * s[6 * 33], 32.f * s[7 * 33]);
;             *(u32x2*)((unsigned char*)WT + (size_t)(drow0 + n) * K + k0 + 8 * c) = o8; }
;         else { u32x4 o; o.x = cvt_pk(s[0 * 33], s[1 * 33]); o.y = cvt_pk(s[2 * 33], s[3 * 33]); o.z = cvt_pk(s[4 * 33], s[5 * 33]); o.w = cvt_pk(s[6 * 33], s[7 * 33]);
;             *(u32x4*)(WT + (size_t)(drow0 + n) * K + k0 + 8 * c) = o; } }
	v_lshl_add_u64 v[56:57], v[56:57], 2, s[20:21]
	global_load_dword v60, v[56:57], off nt
	global_load_dword v61, v[56:57], off offset:8 nt
	global_load_dword v86, v[56:57], off offset:16 nt
	global_load_dword v87, v[56:57], off offset:24 nt
	global_load_dword v88, v[56:57], off offset:32 nt
	global_load_dword v89, v[56:57], off offset:40 nt
	global_load_dword v90, v[56:57], off offset:48 nt
	global_load_dword v91, v[56:57], off offset:56 nt
	global_load_dword v92, v[56:57], off offset:64 nt
	global_load_dword v93, v[56:57], off offset:72 nt
	global_load_dword v94, v[56:57], off offset:80 nt
	global_load_dword v95, v[56:57], off offset:88 nt
	global_load_dword v96, v[56:57], off offset:96 nt
	global_load_dword v97, v[56:57], off offset:104 nt
	global_load_dword v98, v[56:57], off offset:112 nt
	global_load_dword v99, v[56:57], off offset:120 nt
	global_load_dword v100, v[56:57], off offset:128 nt
	global_load_dword v101, v[56:57], off offset:136 nt
	global_load_dword v102, v[56:57], off offset:144 nt
	global_load_dword v103, v[56:57], off offset:152 nt
	global_load_dword v104, v[56:57], off offset:160 nt
	global_load_dword v105, v[56:57], off offset:168 nt
	global_load_dword v106, v[56:57], off offset:176 nt
	global_load_dword v107, v[56:57], off offset:184 nt
	global_load_dword v108, v[56:57], off offset:192 nt
	global_load_dword v109, v[56:57], off offset:200 nt
	global_load_dword v110, v[56:57], off offset:208 nt
	global_load_dword v111, v[56:57], off offset:216 nt
	global_load_dword v112, v[56:57], off offset:224 nt
	global_load_dword v113, v[56:57], off offset:232 nt
	global_load_dword v114, v[56:57], off offset:240 nt
	global_load_dword v115, v[56:57], off offset:248 nt
	s_waitcnt vmcnt(0)
	v_pk_mul_f32 v[34:35], v[34:35], v[60:61]
	v_pk_mul_f32 v[36:37], v[36:37], v[86:87]
	v_pk_mul_f32 v[38:39], v[38:39], v[88:89]
	v_pk_mul_f32 v[40:41], v[40:41], v[90:91]
	v_pk_mul_f32 v[42:43], v[42:43], v[92:93]
	v_pk_mul_f32 v[44:45], v[44:45], v[94:95]
	v_pk_mul_f32 v[46:47], v[46:47], v[96:97]
	v_pk_mul_f32 v[48:49], v[48:49], v[98:99]
	v_pk_mul_f32 v[50:51], v[50:51], v[100:101]
	v_pk_mul_f32 v[52:53], v[52:53], v[102:103]
	v_pk_mul_f32 v[54:55], v[54:55], v[104:105]
	v_pk_mul_f32 v[58:59], v[58:59], v[106:107]
	v_pk_mul_f32 v[62:63], v[62:63], v[108:109]
	v_pk_mul_f32 v[64:65], v[64:65], v[110:111]
	v_pk_mul_f32 v[66:67], v[66:67], v[112:113]
	v_pk_mul_f32 v[68:69], v[68:69], v[114:115]
.LBB0_427:
	s_waitcnt vmcnt(0)
	ds_write2_b32 v71, v34, v35 offset1:66
	ds_write2_b32 v71, v36, v37 offset0:132 offset1:198
	ds_write2_b32 v72, v38, v39 offset0:8 offset1:74
	ds_write2_b32 v72, v40, v41 offset0:140 offset1:206
	ds_write2_b32 v80, v42, v43 offset0:16 offset1:82
	ds_write2_b32 v80, v44, v45 offset0:148 offset1:214
	ds_write2_b32 v82, v46, v47 offset0:24 offset1:90
	ds_write2_b32 v82, v48, v49 offset0:156 offset1:222
	ds_write2_b32 v83, v50, v51 offset0:32 offset1:98
	ds_write2_b32 v83, v52, v53 offset0:164 offset1:230
	ds_write2_b32 v84, v54, v55 offset0:40 offset1:106
	ds_write2_b32 v84, v58, v59 offset0:172 offset1:238
	ds_write2_b32 v85, v62, v63 offset0:48 offset1:114
	ds_write2_b32 v85, v64, v65 offset0:180 offset1:246
	v_add_u32_e32 v34, 0x1c00, v71
	ds_write2_b32 v34, v66, v67 offset0:56 offset1:122
	ds_write2_b32 v34, v68, v69 offset0:188 offset1:254
	s_waitcnt lgkmcnt(0)
	ds_read2_b32 v[38:39], v76 offset0:33 offset1:41
	ds_read2_b32 v[40:41], v76 offset1:8
	ds_read2_b32 v[42:43], v76 offset0:66 offset1:74
	ds_read2_b32 v[44:45], v76 offset0:99 offset1:107
	ds_read2_b32 v[46:47], v76 offset0:132 offset1:140
	ds_read2_b32 v[48:49], v76 offset0:165 offset1:173
	ds_read2_b32 v[50:51], v76 offset0:198 offset1:206
	ds_read2_b32 v[52:53], v76 offset0:231 offset1:239
	v_add_u32_e32 v56, s0, v75
	s_lshl_b32 s68, s1, 1
	v_ashrrev_i32_e32 v57, 31, v56
	v_lshl_add_u64 v[54:55], v[4:5], 0, s[68:69]
	v_lshlrev_b64 v[56:57], 11, v[56:57]
	s_waitcnt lgkmcnt(6)
	v_cvt_pk_bf16_f32 v34, v40, v38
	s_waitcnt lgkmcnt(4)
	v_cvt_pk_bf16_f32 v35, v42, v44
	s_waitcnt lgkmcnt(2)
	v_cvt_pk_bf16_f32 v36, v46, v48
	s_waitcnt lgkmcnt(0)
	v_cvt_pk_bf16_f32 v37, v50, v52
	v_lshl_add_u64 v[56:57], v[54:55], 0, v[56:57]
	v_add_u32_e32 v38, s0, v77
	global_store_dwordx4 v[56:57], v[34:37], off nt
	s_nop 1
	v_cvt_pk_bf16_f32 v34, v41, v39
	v_ashrrev_i32_e32 v39, 31, v38
	v_cvt_pk_bf16_f32 v35, v43, v45
	v_cvt_pk_bf16_f32 v36, v47, v49
	v_cvt_pk_bf16_f32 v37, v51, v53
	v_lshlrev_b64 v[38:39], 11, v[38:39]
	ds_read2_b32 v[40:41], v76 offset0:49 offset1:57
	ds_read2_b32 v[42:43], v76 offset0:16 offset1:24
	ds_read2_b32 v[44:45], v76 offset0:82 offset1:90
	ds_read2_b32 v[46:47], v76 offset0:115 offset1:123
	ds_read2_b32 v[48:49], v76 offset0:148 offset1:156
	ds_read2_b32 v[50:51], v76 offset0:181 offset1:189
	ds_read2_b32 v[52:53], v76 offset0:214 offset1:222
	ds_read2_b32 v[56:57], v76 offset0:247 offset1:255
	v_lshl_add_u64 v[38:39], v[54:55], 0, v[38:39]
	global_store_dwordx4 v[38:39], v[34:37], off nt
	v_add_u32_e32 v38, s0, v78
	v_ashrrev_i32_e32 v39, 31, v38
	v_lshlrev_b64 v[38:39], 11, v[38:39]
	s_waitcnt lgkmcnt(6)
	v_cvt_pk_bf16_f32 v34, v42, v40
	s_waitcnt lgkmcnt(4)
	v_cvt_pk_bf16_f32 v35, v44, v46
	s_waitcnt lgkmcnt(2)
	v_cvt_pk_bf16_f32 v36, v48, v50
	s_waitcnt lgkmcnt(0)
	v_cvt_pk_bf16_f32 v37, v52, v56
	v_lshl_add_u64 v[38:39], v[54:55], 0, v[38:39]
	global_store_dwordx4 v[38:39], v[34:37], off nt
	v_add_u32_e32 v38, s0, v79
	v_ashrrev_i32_e32 v39, 31, v38
	v_lshlrev_b64 v[38:39], 11, v[38:39]
	v_cvt_pk_bf16_f32 v34, v43, v41
	v_cvt_pk_bf16_f32 v35, v45, v47
	v_cvt_pk_bf16_f32 v36, v49, v51
	v_cvt_pk_bf16_f32 v37, v53, v57
	v_lshl_add_u64 v[38:39], v[54:55], 0, v[38:39]
	global_store_dwordx4 v[38:39], v[34:37], off nt
	s_waitcnt lgkmcnt(0)

; template <bool F8 = false>
; __device__ __forceinline__ void p0_transpose_item(const float* W, int K, int N, bf16_t* WT, int k0, int n0, int drow0, const float* gs, LAS float* scr, int lane) {
;     ...
;     for (int i = 0; i < 32; ++i) wv[i] = W[(size_t)(k0 + 2 * i + (lane >> 5)) * N + n0 + (lane & 31)];
; template <int PART>
; __device__ __forceinline__ void phase0(const Ptrs& P, LAS float* scr, int gw, int NGW, int lane) {
;     ...
;         if (r < I_SQ) { const int nblk = DM / 32; p0_transpose_item(P.w_pg, DM, DM, (bf16_t*)(ws + WS_WPG), 64 * (r / nblk), 32 * (r % nblk), 32 * (r % nblk), P.g_ple, scr, lane); continue; } r -= I_SQ;
.LBB0_429:
	s_andn2_b64 vcc, exec, s[0:1]
	s_cbranch_vccnz .LBB0_433
	s_add_i32 s0, s9, 0x2400
	s_and_b32 s1, s0, 0x7fffffc0
	s_and_b32 s0, s8, 0x3e0
	v_add_u32_e32 v56, s1, v70
	s_lshl_b32 s68, s0, 2
	v_ashrrev_i32_e32 v57, 31, v56
	v_lshl_add_u64 v[34:35], v[24:25], 0, s[68:69]
	v_lshlrev_b64 v[36:37], 12, v[56:57]
	v_lshl_add_u64 v[62:63], v[34:35], 0, v[36:37]
	v_add_co_u32_e32 v36, vcc, 0x2000, v62
	global_load_dword v34, v[62:63], off nt
	s_nop 0
	v_addc_co_u32_e32 v37, vcc, 0, v63, vcc
	global_load_dword v35, v[36:37], off nt
	v_add_co_u32_e32 v36, vcc, 0x4000, v62
	v_readlane_b32 s2, v246, 10
	s_nop 0
	v_addc_co_u32_e32 v37, vcc, 0, v63, vcc
	v_add_co_u32_e32 v38, vcc, 0x6000, v62
	global_load_dword v36, v[36:37], off nt
	s_nop 0
	v_addc_co_u32_e32 v39, vcc, 0, v63, vcc
	global_load_dword v37, v[38:39], off nt
	v_add_co_u32_e32 v38, vcc, 0x8000, v62
	v_readlane_b32 s3, v246, 11
	s_nop 0
	v_addc_co_u32_e32 v39, vcc, 0, v63, vcc
	v_add_co_u32_e32 v40, vcc, 0xa000, v62
	global_load_dword v38, v[38:39], off nt
	s_nop 0
	v_addc_co_u32_e32 v41, vcc, 0, v63, vcc
	global_load_dword v39, v[40:41], off nt
	v_add_co_u32_e32 v40, vcc, 0xc000, v62
	s_nop 1
	v_addc_co_u32_e32 v41, vcc, 0, v63, vcc
	v_add_co_u32_e32 v42, vcc, 0xe000, v62
	global_load_dword v40, v[40:41], off nt
	s_nop 0
	v_addc_co_u32_e32 v43, vcc, 0, v63, vcc
	global_load_dword v41, v[42:43], off nt
	v_add_co_u32_e32 v42, vcc, 0x10000, v62
	s_nop 1
	v_addc_co_u32_e32 v43, vcc, 0, v63, vcc
	v_add_co_u32_e32 v44, vcc, 0x12000, v62
	global_load_dword v42, v[42:43], off nt
	s_nop 0
	v_addc_co_u32_e32 v45, vcc, 0, v63, vcc
	global_load_dword v43, v[44:45], off nt
	v_add_co_u32_e32 v44, vcc, 0x14000, v62
	s_nop 1
	v_addc_co_u32_e32 v45, vcc, 0, v63, vcc
	v_add_co_u32_e32 v46, vcc, 0x16000, v62
	global_load_dword v44, v[44:45], off nt
	s_nop 0
	v_addc_co_u32_e32 v47, vcc, 0, v63, vcc
	global_load_dword v45, v[46:47], off nt
	v_add_co_u32_e32 v46, vcc, 0x18000, v62
	s_nop 1
	v_addc_co_u32_e32 v47, vcc, 0, v63, vcc
	v_add_co_u32_e32 v48, vcc, 0x1a000, v62
	global_load_dword v46, v[46:47], off nt
	s_nop 0
	v_addc_co_u32_e32 v49, vcc, 0, v63, vcc
	global_load_dword v47, v[48:49], off nt
	v_add_co_u32_e32 v48, vcc, 0x1c000, v62
	s_nop 1
	v_addc_co_u32_e32 v49, vcc, 0, v63, vcc
	v_add_co_u32_e32 v50, vcc, 0x1e000, v62
	global_load_dword v48, v[48:49], off nt
	s_nop 0
	v_addc_co_u32_e32 v51, vcc, 0, v63, vcc
	global_load_dword v49, v[50:51], off nt
	v_add_co_u32_e32 v50, vcc, 0x20000, v62
	s_nop 1
	v_addc_co_u32_e32 v51, vcc, 0, v63, vcc
	v_add_co_u32_e32 v52, vcc, 0x22000, v62
	global_load_dword v50, v[50:51], off nt
	s_nop 0
	v_addc_co_u32_e32 v53, vcc, 0, v63, vcc
	global_load_dword v51, v[52:53], off nt
	v_add_co_u32_e32 v52, vcc, 0x24000, v62
	s_nop 1
	v_addc_co_u32_e32 v53, vcc, 0, v63, vcc
	v_add_co_u32_e32 v54, vcc, 0x26000, v62
	global_load_dword v52, v[52:53], off nt
	s_nop 0
	v_addc_co_u32_e32 v55, vcc, 0, v63, vcc
	global_load_dword v53, v[54:55], off nt
	v_add_co_u32_e32 v54, vcc, 0x28000, v62
	s_nop 1
	v_addc_co_u32_e32 v55, vcc, 0, v63, vcc
	v_add_co_u32_e32 v58, vcc, 0x2a000, v62
	global_load_dword v54, v[54:55], off nt
	s_nop 0
	v_addc_co_u32_e32 v59, vcc, 0, v63, vcc
	global_load_dword v55, v[58:59], off nt
	v_add_co_u32_e32 v58, vcc, 0x2c000, v62
	s_nop 1
	v_addc_co_u32_e32 v59, vcc, 0, v63, vcc
	v_add_co_u32_e32 v60, vcc, 0x2e000, v62
	global_load_dword v58, v[58:59], off nt
	s_nop 0
	v_addc_co_u32_e32 v61, vcc, 0, v63, vcc
	global_load_dword v59, v[60:61], off nt
	v_add_co_u32_e32 v60, vcc, 0x30000, v62
	s_nop 1
	v_addc_co_u32_e32 v61, vcc, 0, v63, vcc
	v_add_co_u32_e32 v64, vcc, 0x32000, v62
	global_load_dword v60, v[60:61], off nt
	s_nop 0
	v_addc_co_u32_e32 v65, vcc, 0, v63, vcc
	global_load_dword v61, v[64:65], off nt
	v_add_co_u32_e32 v64, vcc, 0x34000, v62
	s_nop 1
	v_addc_co_u32_e32 v65, vcc, 0, v63, vcc
	v_add_co_u32_e32 v66, vcc, 0x36000, v62
	global_load_dword v64, v[64:65], off nt
	s_nop 0
	v_addc_co_u32_e32 v67, vcc, 0, v63, vcc
	global_load_dword v65, v[66:67], off nt
	v_add_co_u32_e32 v66, vcc, 0x38000, v62
	s_nop 1
	v_addc_co_u32_e32 v67, vcc, 0, v63, vcc
	v_add_co_u32_e32 v68, vcc, 0x3a000, v62
	global_load_dword v66, v[66:67], off nt
	s_nop 0
	v_addc_co_u32_e32 v69, vcc, 0, v63, vcc
	global_load_dword v67, v[68:69], off nt
	v_add_co_u32_e32 v68, vcc, 0x3c000, v62
	s_nop 1
	v_addc_co_u32_e32 v69, vcc, 0, v63, vcc
	v_add_co_u32_e32 v62, vcc, 0x3e000, v62
	global_load_dword v68, v[68:69], off nt
	s_nop 0
	v_addc_co_u32_e32 v63, vcc, 0, v63, vcc
	global_load_dword v69, v[62:63], off nt
	s_andn2_b64 vcc, exec, s[2:3]
	s_cbranch_vccnz .LBB0_432
; #define LAS __attribute__((address_space(3)))
; __device__ __forceinline__ unsigned cvt_pk(float lo, float hi) { f32x2_t v = {lo, hi}; bf16x2_t b = __builtin_convertvector(v, bf16x2_t); return __builtin_bit_cast(unsigned, b); }
; __device__ __forceinline__ unsigned pk_fp8x4(float a, float b, float c, float d) { int w = 0; w = __builtin_amdgcn_cvt_pk_fp8_f32(a, b, w, false); w = __builtin_amdgcn_cvt_pk_fp8_f32(c, d, w, true); return (unsigned)w; }
; template <bool F8 = false>
; __device__ __forceinline__ void p0_transpose_item(const float* W, int K, int N, bf16_t* WT, int k0, int n0, int drow0, const float* gs, LAS float* scr, int lane) {
;     ...
;     for (int i = 0; i < 32; ++i) wv[i] = W[(size_t)(k0 + 2 * i + (lane >> 5)) * N + n0 + (lane & 31)];
;     if (gs) {
; #pragma unroll
;         for (int i = 0; i < 32; ++i) wv[i] *= gs[k0 + 2 * i + (lane >> 5)]; }
; #pragma unroll
;     for (int i = 0; i < 32; ++i) scr[(2 * i + (lane >> 5)) * 33 + (lane & 31)] = wv[i];
;     asm volatile("s_waitcnt lgkmcnt(0)" ::: "memory");
;     const int c = lane & 7;
; #pragma unroll
;     for (int j = 0; j < 4; ++j) { const int n = (lane >> 3) + 8 * j; const LAS float* s = scr + (8 * c) * 33 + n;
;         if (F8) { u32x2 o8; o8.x = pk_fp8x4(32.f * s[0 * 33], 32.f * s[1 * 33], 32.f * s[2 * 33], 32.f * s[3 * 33]); o8.y = pk_fp8x4(32.f * s[4 * 33], 32.f * s[5 * 33], 32.f * s[6 * 33], 32.f * s[7 * 33]);
;             *(u32x2*)((unsigned char*)WT + (size_t)(drow0 + n) * K + k0 + 8 * c) = o8; }
;         else { u32x4 o; o.x = cvt_pk(s[0 * 33], s[1 * 33]); o.y = cvt_pk(s[2 * 33], s[3 * 33]); o.z = cvt_pk(s[4 * 33], s[5 * 33]); o.w = cvt_pk(s[6 * 33], s[7 * 33]);
;             *(u32x4*)(WT + (size_t)(drow0 + n) * K + k0 + 8 * c) = o; } }
	v_readlane_b32 s48, v247, 0
	v_readlane_b32 s50, v247, 2
	v_readlane_b32 s51, v247, 3
	v_readlane_b32 s49, v247, 1
	v_readlane_b32 s52, v247, 4
	v_lshl_add_u64 v[56:57], v[56:57], 2, s[50:51]
	global_load_dword v62, v[56:57], off nt
	global_load_dword v63, v[56:57], off offset:8 nt
	global_load_dword v86, v[56:57], off offset:16 nt
	global_load_dword v87, v[56:57], off offset:24 nt
	global_load_dword v88, v[56:57], off offset:32 nt
	global_load_dword v89, v[56:57], off offset:40 nt
	global_load_dword v90, v[56:57], off offset:48 nt
	global_load_dword v91, v[56:57], off offset:56 nt
	global_load_dword v92, v[56:57], off offset:64 nt
	global_load_dword v93, v[56:57], off offset:72 nt
	global_load_dword v94, v[56:57], off offset:80 nt
	global_load_dword v95, v[56:57], off offset:88 nt
	global_load_dword v96, v[56:57], off offset:96 nt
	global_load_dword v97, v[56:57], off offset:104 nt
	global_load_dword v98, v[56:57], off offset:112 nt
	global_load_dword v99, v[56:57], off offset:120 nt
	global_load_dword v100, v[56:57], off offset:128 nt
	global_load_dword v101, v[56:57], off offset:136 nt
	global_load_dword v102, v[56:57], off offset:144 nt
	global_load_dword v103, v[56:57], off offset:152 nt
	global_load_dword v104, v[56:57], off offset:160 nt
	global_load_dword v105, v[56:57], off offset:168 nt
	global_load_dword v106, v[56:57], off offset:176 nt
	global_load_dword v107, v[56:57], off offset:184 nt
	global_load_dword v108, v[56:57], off offset:192 nt
	global_load_dword v109, v[56:57], off offset:200 nt
	global_load_dword v110, v[56:57], off offset:208 nt
	global_load_dword v111, v[56:57], off offset:216 nt
	global_load_dword v112, v[56:57], off offset:224 nt
	global_load_dword v113, v[56:57], off offset:232 nt
	global_load_dword v114, v[56:57], off offset:240 nt
	global_load_dword v115, v[56:57], off offset:248 nt
	v_readlane_b32 s53, v247, 5
	v_readlane_b32 s54, v247, 6
	v_readlane_b32 s55, v247, 7
	s_waitcnt vmcnt(0)
	v_pk_mul_f32 v[34:35], v[34:35], v[62:63]
	v_pk_mul_f32 v[36:37], v[36:37], v[86:87]
	v_pk_mul_f32 v[38:39], v[38:39], v[88:89]
	v_pk_mul_f32 v[40:41], v[40:41], v[90:91]
	v_pk_mul_f32 v[42:43], v[42:43], v[92:93]
	v_pk_mul_f32 v[44:45], v[44:45], v[94:95]
	v_pk_mul_f32 v[46:47], v[46:47], v[96:97]
	v_pk_mul_f32 v[48:49], v[48:49], v[98:99]
	v_pk_mul_f32 v[50:51], v[50:51], v[100:101]
	v_pk_mul_f32 v[52:53], v[52:53], v[102:103]
	v_pk_mul_f32 v[54:55], v[54:55], v[104:105]
	v_pk_mul_f32 v[58:59], v[58:59], v[106:107]
	v_pk_mul_f32 v[60:61], v[60:61], v[108:109]
	v_pk_mul_f32 v[64:65], v[64:65], v[110:111]
	v_pk_mul_f32 v[66:67], v[66:67], v[112:113]
	v_pk_mul_f32 v[68:69], v[68:69], v[114:115]
.LBB0_432:
	s_waitcnt vmcnt(0)
	ds_write2_b32 v71, v34, v35 offset1:66
	ds_write2_b32 v71, v36, v37 offset0:132 offset1:198
	ds_write2_b32 v72, v38, v39 offset0:8 offset1:74
	ds_write2_b32 v72, v40, v41 offset0:140 offset1:206
	ds_write2_b32 v80, v42, v43 offset0:16 offset1:82
	ds_write2_b32 v80, v44, v45 offset0:148 offset1:214
	ds_write2_b32 v82, v46, v47 offset0:24 offset1:90
	ds_write2_b32 v82, v48, v49 offset0:156 offset1:222
	ds_write2_b32 v83, v50, v51 offset0:32 offset1:98
	ds_write2_b32 v83, v52, v53 offset0:164 offset1:230
	ds_write2_b32 v84, v54, v55 offset0:40 offset1:106
	ds_write2_b32 v84, v58, v59 offset0:172 offset1:238
	ds_write2_b32 v85, v60, v61 offset0:48 offset1:114
	ds_write2_b32 v85, v64, v65 offset0:180 offset1:246
	v_add_u32_e32 v34, 0x1c00, v71
	ds_write2_b32 v34, v66, v67 offset0:56 offset1:122
	ds_write2_b32 v34, v68, v69 offset0:188 offset1:254
	s_waitcnt lgkmcnt(0)
	ds_read2_b32 v[38:39], v76 offset0:33 offset1:41
	ds_read2_b32 v[40:41], v76 offset1:8
	ds_read2_b32 v[42:43], v76 offset0:66 offset1:74
	ds_read2_b32 v[44:45], v76 offset0:99 offset1:107
	ds_read2_b32 v[46:47], v76 offset0:132 offset1:140
	ds_read2_b32 v[48:49], v76 offset0:165 offset1:173
	ds_read2_b32 v[50:51], v76 offset0:198 offset1:206
	ds_read2_b32 v[52:53], v76 offset0:231 offset1:239
	v_add_u32_e32 v56, s0, v75
	s_lshl_b32 s68, s1, 1
	v_ashrrev_i32_e32 v57, 31, v56
	v_lshl_add_u64 v[54:55], v[6:7], 0, s[68:69]
	v_lshlrev_b64 v[56:57], 11, v[56:57]
	s_waitcnt lgkmcnt(6)
	v_cvt_pk_bf16_f32 v34, v40, v38
	s_waitcnt lgkmcnt(4)
	v_cvt_pk_bf16_f32 v35, v42, v44
	s_waitcnt lgkmcnt(2)
	v_cvt_pk_bf16_f32 v36, v46, v48
	s_waitcnt lgkmcnt(0)
	v_cvt_pk_bf16_f32 v37, v50, v52
	v_lshl_add_u64 v[56:57], v[54:55], 0, v[56:57]
	v_add_u32_e32 v38, s0, v77
	global_store_dwordx4 v[56:57], v[34:37], off nt
	s_nop 1
	v_cvt_pk_bf16_f32 v34, v41, v39
	v_ashrrev_i32_e32 v39, 31, v38
	v_cvt_pk_bf16_f32 v35, v43, v45
	v_cvt_pk_bf16_f32 v36, v47, v49
	v_cvt_pk_bf16_f32 v37, v51, v53
	v_lshlrev_b64 v[38:39], 11, v[38:39]
	ds_read2_b32 v[40:41], v76 offset0:49 offset1:57
	ds_read2_b32 v[42:43], v76 offset0:16 offset1:24
	ds_read2_b32 v[44:45], v76 offset0:82 offset1:90
	ds_read2_b32 v[46:47], v76 offset0:115 offset1:123
	ds_read2_b32 v[48:49], v76 offset0:148 offset1:156
	ds_read2_b32 v[50:51], v76 offset0:181 offset1:189
	ds_read2_b32 v[52:53], v76 offset0:214 offset1:222
	ds_read2_b32 v[56:57], v76 offset0:247 offset1:255
	v_lshl_add_u64 v[38:39], v[54:55], 0, v[38:39]
	global_store_dwordx4 v[38:39], v[34:37], off nt
	v_add_u32_e32 v38, s0, v78
	v_ashrrev_i32_e32 v39, 31, v38
	v_lshlrev_b64 v[38:39], 11, v[38:39]
	s_waitcnt lgkmcnt(6)
	v_cvt_pk_bf16_f32 v34, v42, v40
	s_waitcnt lgkmcnt(4)
	v_cvt_pk_bf16_f32 v35, v44, v46
	s_waitcnt lgkmcnt(2)
	v_cvt_pk_bf16_f32 v36, v48, v50
	s_waitcnt lgkmcnt(0)
	v_cvt_pk_bf16_f32 v37, v52, v56
	v_lshl_add_u64 v[38:39], v[54:55], 0, v[38:39]
	global_store_dwordx4 v[38:39], v[34:37], off nt
	v_add_u32_e32 v38, s0, v79
	v_ashrrev_i32_e32 v39, 31, v38
	v_lshlrev_b64 v[38:39], 11, v[38:39]
	v_cvt_pk_bf16_f32 v34, v43, v41
	v_cvt_pk_bf16_f32 v35, v45, v47
	v_cvt_pk_bf16_f32 v36, v49, v51
	v_cvt_pk_bf16_f32 v37, v53, v57
	v_lshl_add_u64 v[38:39], v[54:55], 0, v[38:39]
	global_store_dwordx4 v[38:39], v[34:37], off nt
	s_waitcnt lgkmcnt(0)

; #define LAS __attribute__((address_space(3)))
; template <bool F8 = false>
; __device__ __forceinline__ void p0_transpose_item(const float* W, int K, int N, bf16_t* WT, int k0, int n0, int drow0, const float* gs, LAS float* scr, int lane) {
;     float wv[32];
; #pragma unroll
;     for (int i = 0; i < 32; ++i) wv[i] = W[(size_t)(k0 + 2 * i + (lane >> 5)) * N + n0 + (lane & 31)];
; template <int PART>
; __device__ __forceinline__ void phase0(const Ptrs& P, LAS float* scr, int gw, int NGW, int lane) {
;     ...
;         if (r < I_SQ) { const int nblk = DM / 32; p0_transpose_item(P.w_brl, DM, DM, (bf16_t*)(ws + WS_WBRL), 64 * (r / nblk), 32 * (r % nblk), 32 * (r % nblk), nullptr, scr, lane); continue; } r -= I_SQ;
;         if (r < I_SQ) { const int nblk = DM / 32; p0_transpose_item(P.w_bra, DM, DM, (bf16_t*)(ws + WS_WBRA), 64 * (r / nblk), 32 * (r % nblk), 32 * (r % nblk), nullptr, scr, lane); continue; } r -= I_SQ;
;         if (r < I_SQ) { const int nblk = DM / 32; p0_transpose_item(P.w_out, DM, DM, (bf16_t*)(ws + WS_WOUT), 64 * (r / nblk), 32 * (r % nblk), 32 * (r % nblk), nullptr, scr, lane); continue; } r -= I_SQ;
.LBB0_434:
	s_andn2_b64 vcc, exec, s[0:1]
	s_cbranch_vccnz .LBB0_436
	s_add_i32 s0, s9, 0x2800
	s_and_b32 s1, s0, 0x7fffffc0
	s_and_b32 s0, s8, 0x3e0
	v_add_u32_e32 v34, s1, v70
	s_lshl_b32 s68, s0, 2
	v_ashrrev_i32_e32 v35, 31, v34
	v_lshl_add_u64 v[36:37], v[26:27], 0, s[68:69]
	v_lshlrev_b64 v[34:35], 12, v[34:35]
	v_lshl_add_u64 v[34:35], v[36:37], 0, v[34:35]
	v_add_co_u32_e32 v36, vcc, 0x2000, v34
	global_load_dword v38, v[34:35], off nt
	s_nop 0
	v_addc_co_u32_e32 v37, vcc, 0, v35, vcc
	global_load_dword v39, v[36:37], off nt
	v_add_co_u32_e32 v36, vcc, 0x4000, v34
	s_lshl_b32 s68, s1, 1
	s_nop 0
	v_addc_co_u32_e32 v37, vcc, 0, v35, vcc
	global_load_dword v40, v[36:37], off nt
	v_add_co_u32_e32 v36, vcc, 0x6000, v34
	s_nop 1
	v_addc_co_u32_e32 v37, vcc, 0, v35, vcc
	global_load_dword v41, v[36:37], off nt
	v_add_co_u32_e32 v36, vcc, 0x8000, v34
	s_nop 1
	v_addc_co_u32_e32 v37, vcc, 0, v35, vcc
	global_load_dword v42, v[36:37], off nt
	v_add_co_u32_e32 v36, vcc, 0xa000, v34
	s_nop 1
	v_addc_co_u32_e32 v37, vcc, 0, v35, vcc
	global_load_dword v43, v[36:37], off nt
	v_add_co_u32_e32 v36, vcc, 0xc000, v34
	s_nop 1
	v_addc_co_u32_e32 v37, vcc, 0, v35, vcc
	global_load_dword v44, v[36:37], off nt
	v_add_co_u32_e32 v36, vcc, 0xe000, v34
	s_nop 1
	v_addc_co_u32_e32 v37, vcc, 0, v35, vcc
	global_load_dword v45, v[36:37], off nt
	v_add_co_u32_e32 v36, vcc, 0x10000, v34
	s_nop 1
	v_addc_co_u32_e32 v37, vcc, 0, v35, vcc
	global_load_dword v46, v[36:37], off nt
	v_add_co_u32_e32 v36, vcc, 0x12000, v34
	s_nop 1
	v_addc_co_u32_e32 v37, vcc, 0, v35, vcc
	global_load_dword v47, v[36:37], off nt
	v_add_co_u32_e32 v36, vcc, 0x14000, v34
	s_nop 1
	v_addc_co_u32_e32 v37, vcc, 0, v35, vcc
	global_load_dword v48, v[36:37], off nt
	v_add_co_u32_e32 v36, vcc, 0x16000, v34
	s_nop 1
	v_addc_co_u32_e32 v37, vcc, 0, v35, vcc
	global_load_dword v49, v[36:37], off nt
	v_add_co_u32_e32 v36, vcc, 0x18000, v34
	s_nop 1
	v_addc_co_u32_e32 v37, vcc, 0, v35, vcc
	global_load_dword v50, v[36:37], off nt
	v_add_co_u32_e32 v36, vcc, 0x1a000, v34
	s_nop 1
	v_addc_co_u32_e32 v37, vcc, 0, v35, vcc
	global_load_dword v51, v[36:37], off nt
	v_add_co_u32_e32 v36, vcc, 0x1c000, v34
	s_nop 1
	v_addc_co_u32_e32 v37, vcc, 0, v35, vcc
	global_load_dword v52, v[36:37], off nt
	v_add_co_u32_e32 v36, vcc, 0x1e000, v34
	s_nop 1
	v_addc_co_u32_e32 v37, vcc, 0, v35, vcc
	global_load_dword v53, v[36:37], off nt
	v_add_co_u32_e32 v36, vcc, 0x20000, v34
	s_nop 1
	v_addc_co_u32_e32 v37, vcc, 0, v35, vcc
	global_load_dword v54, v[36:37], off nt
	v_add_co_u32_e32 v36, vcc, 0x22000, v34
	s_nop 1
	v_addc_co_u32_e32 v37, vcc, 0, v35, vcc
	global_load_dword v55, v[36:37], off nt
	v_add_co_u32_e32 v36, vcc, 0x24000, v34
	s_nop 1
	v_addc_co_u32_e32 v37, vcc, 0, v35, vcc
	global_load_dword v56, v[36:37], off nt
	v_add_co_u32_e32 v36, vcc, 0x26000, v34
	s_nop 1
	v_addc_co_u32_e32 v37, vcc, 0, v35, vcc
	global_load_dword v57, v[36:37], off nt
	v_add_co_u32_e32 v36, vcc, 0x28000, v34
	s_nop 1
	v_addc_co_u32_e32 v37, vcc, 0, v35, vcc
	global_load_dword v58, v[36:37], off nt
	v_add_co_u32_e32 v36, vcc, 0x2a000, v34
	s_nop 1
	v_addc_co_u32_e32 v37, vcc, 0, v35, vcc
	global_load_dword v59, v[36:37], off nt
	v_add_co_u32_e32 v36, vcc, 0x2c000, v34
	s_nop 1
	v_addc_co_u32_e32 v37, vcc, 0, v35, vcc
	global_load_dword v60, v[36:37], off nt
	v_add_co_u32_e32 v36, vcc, 0x2e000, v34
	s_nop 1
	v_addc_co_u32_e32 v37, vcc, 0, v35, vcc
	global_load_dword v61, v[36:37], off nt
	v_add_co_u32_e32 v36, vcc, 0x30000, v34
	s_nop 1
	v_addc_co_u32_e32 v37, vcc, 0, v35, vcc
	global_load_dword v62, v[36:37], off nt
	v_add_co_u32_e32 v36, vcc, 0x32000, v34
	s_nop 1
	v_addc_co_u32_e32 v37, vcc, 0, v35, vcc
	global_load_dword v63, v[36:37], off nt
	v_add_co_u32_e32 v36, vcc, 0x34000, v34
	s_nop 1
	v_addc_co_u32_e32 v37, vcc, 0, v35, vcc
	global_load_dword v64, v[36:37], off nt
	v_add_co_u32_e32 v36, vcc, 0x36000, v34
	s_nop 1
	v_addc_co_u32_e32 v37, vcc, 0, v35, vcc
	global_load_dword v65, v[36:37], off nt
	v_add_co_u32_e32 v36, vcc, 0x38000, v34
	s_nop 1
	v_addc_co_u32_e32 v37, vcc, 0, v35, vcc
	global_load_dword v66, v[36:37], off nt
	v_add_co_u32_e32 v36, vcc, 0x3a000, v34
	s_nop 1
	v_addc_co_u32_e32 v37, vcc, 0, v35, vcc
	global_load_dword v67, v[36:37], off nt
	v_add_co_u32_e32 v36, vcc, 0x3c000, v34
	s_nop 1
	v_addc_co_u32_e32 v37, vcc, 0, v35, vcc
	v_add_co_u32_e32 v34, vcc, 0x3e000, v34
	global_load_dword v36, v[36:37], off nt
	s_nop 0
	v_addc_co_u32_e32 v35, vcc, 0, v35, vcc
	global_load_dword v34, v[34:35], off nt
	v_add_u32_e32 v35, 0x1c00, v71
	s_waitcnt vmcnt(0)
; #define LAS __attribute__((address_space(3)))
; __device__ __forceinline__ unsigned cvt_pk(float lo, float hi) { f32x2_t v = {lo, hi}; bf16x2_t b = __builtin_convertvector(v, bf16x2_t); return __builtin_bit_cast(unsigned, b); }
; __device__ __forceinline__ unsigned pk_fp8x4(float a, float b, float c, float d) { int w = 0; w = __builtin_amdgcn_cvt_pk_fp8_f32(a, b, w, false); w = __builtin_amdgcn_cvt_pk_fp8_f32(c, d, w, true); return (unsigned)w; }
; template <bool F8 = false>
; __device__ __forceinline__ void p0_transpose_item(const float* W, int K, int N, bf16_t* WT, int k0, int n0, int drow0, const float* gs, LAS float* scr, int lane) {
;     ...
;     for (int i = 0; i < 32; ++i) scr[(2 * i + (lane >> 5)) * 33 + (lane & 31)] = wv[i];
;     asm volatile("s_waitcnt lgkmcnt(0)" ::: "memory");
;     const int c = lane & 7;
; #pragma unroll
;     for (int j = 0; j < 4; ++j) { const int n = (lane >> 3) + 8 * j; const LAS float* s = scr + (8 * c) * 33 + n;
;         if (F8) { u32x2 o8; o8.x = pk_fp8x4(32.f * s[0 * 33], 32.f * s[1 * 33], 32.f * s[2 * 33], 32.f * s[3 * 33]); o8.y = pk_fp8x4(32.f * s[4 * 33], 32.f * s[5 * 33], 32.f * s[6 * 33], 32.f * s[7 * 33]);
;             *(u32x2*)((unsigned char*)WT + (size_t)(drow0 + n) * K + k0 + 8 * c) = o8; }
;         else { u32x4 o; o.x = cvt_pk(s[0 * 33], s[1 * 33]); o.y = cvt_pk(s[2 * 33], s[3 * 33]); o.z = cvt_pk(s[4 * 33], s[5 * 33]); o.w = cvt_pk(s[6 * 33], s[7 * 33]);
;             *(u32x4*)(WT + (size_t)(drow0 + n) * K + k0 + 8 * c) = o; } }
	ds_write2_b32 v71, v38, v39 offset1:66
	ds_write2_b32 v71, v40, v41 offset0:132 offset1:198
	ds_write2_b32 v72, v42, v43 offset0:8 offset1:74
	ds_write2_b32 v72, v44, v45 offset0:140 offset1:206
	ds_write2_b32 v80, v46, v47 offset0:16 offset1:82
	ds_write2_b32 v80, v48, v49 offset0:148 offset1:214
	ds_write2_b32 v82, v50, v51 offset0:24 offset1:90
	ds_write2_b32 v82, v52, v53 offset0:156 offset1:222
	ds_write2_b32 v83, v54, v55 offset0:32 offset1:98
	ds_write2_b32 v83, v56, v57 offset0:164 offset1:230
	ds_write2_b32 v84, v58, v59 offset0:40 offset1:106
	ds_write2_b32 v84, v60, v61 offset0:172 offset1:238
	ds_write2_b32 v85, v62, v63 offset0:48 offset1:114
	ds_write2_b32 v85, v64, v65 offset0:180 offset1:246
	ds_write2_b32 v35, v66, v67 offset0:56 offset1:122
	ds_write2_b32 v35, v36, v34 offset0:188 offset1:254
	s_waitcnt lgkmcnt(0)
	ds_read2_b32 v[40:41], v76 offset0:33 offset1:41
	ds_read2_b32 v[42:43], v76 offset1:8
	ds_read2_b32 v[44:45], v76 offset0:66 offset1:74
	ds_read2_b32 v[46:47], v76 offset0:99 offset1:107
	ds_read2_b32 v[48:49], v76 offset0:132 offset1:140
	ds_read2_b32 v[50:51], v76 offset0:165 offset1:173
	ds_read2_b32 v[52:53], v76 offset0:198 offset1:206
	ds_read2_b32 v[54:55], v76 offset0:231 offset1:239
	v_add_u32_e32 v56, s0, v75
	v_ashrrev_i32_e32 v57, 31, v56
	v_lshl_add_u64 v[38:39], v[8:9], 0, s[68:69]
	v_lshlrev_b64 v[56:57], 11, v[56:57]
	s_waitcnt lgkmcnt(6)
	v_cvt_pk_bf16_f32 v34, v42, v40
	s_waitcnt lgkmcnt(4)
	v_cvt_pk_bf16_f32 v35, v44, v46
	s_waitcnt lgkmcnt(2)
	v_cvt_pk_bf16_f32 v36, v48, v50
	s_waitcnt lgkmcnt(0)
	v_cvt_pk_bf16_f32 v37, v52, v54
	v_lshl_add_u64 v[56:57], v[38:39], 0, v[56:57]
	v_add_u32_e32 v40, s0, v77
	global_store_dwordx4 v[56:57], v[34:37], off nt
	v_add_u32_e32 v56, s0, v78
	v_ashrrev_i32_e32 v57, 31, v56
	v_cvt_pk_bf16_f32 v34, v43, v41
	v_ashrrev_i32_e32 v41, 31, v40
	v_lshlrev_b64 v[40:41], 11, v[40:41]
	v_cvt_pk_bf16_f32 v35, v45, v47
	v_cvt_pk_bf16_f32 v36, v49, v51
	v_cvt_pk_bf16_f32 v37, v53, v55
	v_lshl_add_u64 v[40:41], v[38:39], 0, v[40:41]
	global_store_dwordx4 v[40:41], v[34:37], off nt
	ds_read2_b32 v[40:41], v76 offset0:49 offset1:57
	ds_read2_b32 v[42:43], v76 offset0:16 offset1:24
	ds_read2_b32 v[44:45], v76 offset0:82 offset1:90
	ds_read2_b32 v[46:47], v76 offset0:115 offset1:123
	ds_read2_b32 v[48:49], v76 offset0:148 offset1:156
	ds_read2_b32 v[50:51], v76 offset0:181 offset1:189
	ds_read2_b32 v[52:53], v76 offset0:214 offset1:222
	ds_read2_b32 v[54:55], v76 offset0:247 offset1:255
	v_lshlrev_b64 v[56:57], 11, v[56:57]
	s_waitcnt lgkmcnt(6)
	v_cvt_pk_bf16_f32 v34, v42, v40
	s_waitcnt lgkmcnt(4)
	v_cvt_pk_bf16_f32 v35, v44, v46
	s_waitcnt lgkmcnt(2)
	v_cvt_pk_bf16_f32 v36, v48, v50
	s_waitcnt lgkmcnt(0)
	v_cvt_pk_bf16_f32 v37, v52, v54
	v_lshl_add_u64 v[56:57], v[38:39], 0, v[56:57]
	v_add_u32_e32 v40, s0, v79
	global_store_dwordx4 v[56:57], v[34:37], off nt
	s_nop 1
	v_cvt_pk_bf16_f32 v34, v43, v41
	v_ashrrev_i32_e32 v41, 31, v40
	v_lshlrev_b64 v[40:41], 11, v[40:41]
	v_cvt_pk_bf16_f32 v35, v45, v47
	v_cvt_pk_bf16_f32 v36, v49, v51
	v_cvt_pk_bf16_f32 v37, v53, v55
	v_lshl_add_u64 v[38:39], v[38:39], 0, v[40:41]
	global_store_dwordx4 v[38:39], v[34:37], off nt
	s_waitcnt lgkmcnt(0)

; #define LAS __attribute__((address_space(3)))
; template <bool F8 = false>
; __device__ __forceinline__ void p0_transpose_item(const float* W, int K, int N, bf16_t* WT, int k0, int n0, int drow0, const float* gs, LAS float* scr, int lane) {
;     float wv[32];
; #pragma unroll
;     for (int i = 0; i < 32; ++i) wv[i] = W[(size_t)(k0 + 2 * i + (lane >> 5)) * N + n0 + (lane & 31)];
; template <int PART>
; __device__ __forceinline__ void phase0(const Ptrs& P, LAS float* scr, int gw, int NGW, int lane) {
;     ...
;         if (r < I_SQ) { const int nblk = DM / 32; p0_transpose_item(P.w_brl, DM, DM, (bf16_t*)(ws + WS_WBRL), 64 * (r / nblk), 32 * (r % nblk), 32 * (r % nblk), nullptr, scr, lane); continue; } r -= I_SQ;
;         if (r < I_SQ) { const int nblk = DM / 32; p0_transpose_item(P.w_bra, DM, DM, (bf16_t*)(ws + WS_WBRA), 64 * (r / nblk), 32 * (r % nblk), 32 * (r % nblk), nullptr, scr, lane); continue; } r -= I_SQ;
;         if (r < I_SQ) { const int nblk = DM / 32; p0_transpose_item(P.w_out, DM, DM, (bf16_t*)(ws + WS_WOUT), 64 * (r / nblk), 32 * (r % nblk), 32 * (r % nblk), nullptr, scr, lane); continue; } r -= I_SQ;
.LBB0_437:
	s_andn2_b64 vcc, exec, s[0:1]
	s_cbranch_vccnz .LBB0_439
	s_add_i32 s0, s9, 0x2c00
	s_and_b32 s1, s0, 0x7fffffc0
	s_and_b32 s0, s8, 0x3e0
	v_add_u32_e32 v34, s1, v70
	s_lshl_b32 s68, s0, 2
	v_ashrrev_i32_e32 v35, 31, v34
	v_lshl_add_u64 v[36:37], v[28:29], 0, s[68:69]
	v_lshlrev_b64 v[34:35], 12, v[34:35]
	v_lshl_add_u64 v[34:35], v[36:37], 0, v[34:35]
	v_add_co_u32_e32 v36, vcc, 0x2000, v34
	global_load_dword v38, v[34:35], off nt
	s_nop 0
	v_addc_co_u32_e32 v37, vcc, 0, v35, vcc
	global_load_dword v39, v[36:37], off nt
	v_add_co_u32_e32 v36, vcc, 0x4000, v34
	s_lshl_b32 s68, s1, 1
	s_nop 0
	v_addc_co_u32_e32 v37, vcc, 0, v35, vcc
	global_load_dword v40, v[36:37], off nt
	v_add_co_u32_e32 v36, vcc, 0x6000, v34
	s_nop 1
	v_addc_co_u32_e32 v37, vcc, 0, v35, vcc
	global_load_dword v41, v[36:37], off nt
	v_add_co_u32_e32 v36, vcc, 0x8000, v34
	s_nop 1
	v_addc_co_u32_e32 v37, vcc, 0, v35, vcc
	global_load_dword v42, v[36:37], off nt
	v_add_co_u32_e32 v36, vcc, 0xa000, v34
	s_nop 1
	v_addc_co_u32_e32 v37, vcc, 0, v35, vcc
	global_load_dword v43, v[36:37], off nt
	v_add_co_u32_e32 v36, vcc, 0xc000, v34
	s_nop 1
	v_addc_co_u32_e32 v37, vcc, 0, v35, vcc
	global_load_dword v44, v[36:37], off nt
	v_add_co_u32_e32 v36, vcc, 0xe000, v34
	s_nop 1
	v_addc_co_u32_e32 v37, vcc, 0, v35, vcc
	global_load_dword v45, v[36:37], off nt
	v_add_co_u32_e32 v36, vcc, 0x10000, v34
	s_nop 1
	v_addc_co_u32_e32 v37, vcc, 0, v35, vcc
	global_load_dword v46, v[36:37], off nt
	v_add_co_u32_e32 v36, vcc, 0x12000, v34
	s_nop 1
	v_addc_co_u32_e32 v37, vcc, 0, v35, vcc
	global_load_dword v47, v[36:37], off nt
	v_add_co_u32_e32 v36, vcc, 0x14000, v34
	s_nop 1
	v_addc_co_u32_e32 v37, vcc, 0, v35, vcc
	global_load_dword v48, v[36:37], off nt
	v_add_co_u32_e32 v36, vcc, 0x16000, v34
	s_nop 1
	v_addc_co_u32_e32 v37, vcc, 0, v35, vcc
	global_load_dword v49, v[36:37], off nt
	v_add_co_u32_e32 v36, vcc, 0x18000, v34
	s_nop 1
	v_addc_co_u32_e32 v37, vcc, 0, v35, vcc
	global_load_dword v50, v[36:37], off nt
	v_add_co_u32_e32 v36, vcc, 0x1a000, v34
	s_nop 1
	v_addc_co_u32_e32 v37, vcc, 0, v35, vcc
	global_load_dword v51, v[36:37], off nt
	v_add_co_u32_e32 v36, vcc, 0x1c000, v34
	s_nop 1
	v_addc_co_u32_e32 v37, vcc, 0, v35, vcc
	global_load_dword v52, v[36:37], off nt
	v_add_co_u32_e32 v36, vcc, 0x1e000, v34
	s_nop 1
	v_addc_co_u32_e32 v37, vcc, 0, v35, vcc
	global_load_dword v53, v[36:37], off nt
	v_add_co_u32_e32 v36, vcc, 0x20000, v34
	s_nop 1
	v_addc_co_u32_e32 v37, vcc, 0, v35, vcc
	global_load_dword v54, v[36:37], off nt
	v_add_co_u32_e32 v36, vcc, 0x22000, v34
	s_nop 1
	v_addc_co_u32_e32 v37, vcc, 0, v35, vcc
	global_load_dword v55, v[36:37], off nt
	v_add_co_u32_e32 v36, vcc, 0x24000, v34
	s_nop 1
	v_addc_co_u32_e32 v37, vcc, 0, v35, vcc
	global_load_dword v56, v[36:37], off nt
	v_add_co_u32_e32 v36, vcc, 0x26000, v34
	s_nop 1
	v_addc_co_u32_e32 v37, vcc, 0, v35, vcc
	global_load_dword v57, v[36:37], off nt
	v_add_co_u32_e32 v36, vcc, 0x28000, v34
	s_nop 1
	v_addc_co_u32_e32 v37, vcc, 0, v35, vcc
	global_load_dword v58, v[36:37], off nt
	v_add_co_u32_e32 v36, vcc, 0x2a000, v34
	s_nop 1
	v_addc_co_u32_e32 v37, vcc, 0, v35, vcc
	global_load_dword v59, v[36:37], off nt
	v_add_co_u32_e32 v36, vcc, 0x2c000, v34
	s_nop 1
	v_addc_co_u32_e32 v37, vcc, 0, v35, vcc
	global_load_dword v60, v[36:37], off nt
	v_add_co_u32_e32 v36, vcc, 0x2e000, v34
	s_nop 1
	v_addc_co_u32_e32 v37, vcc, 0, v35, vcc
	global_load_dword v61, v[36:37], off nt
	v_add_co_u32_e32 v36, vcc, 0x30000, v34
	s_nop 1
	v_addc_co_u32_e32 v37, vcc, 0, v35, vcc
	global_load_dword v62, v[36:37], off nt
	v_add_co_u32_e32 v36, vcc, 0x32000, v34
	s_nop 1
	v_addc_co_u32_e32 v37, vcc, 0, v35, vcc
	global_load_dword v63, v[36:37], off nt
	v_add_co_u32_e32 v36, vcc, 0x34000, v34
	s_nop 1
	v_addc_co_u32_e32 v37, vcc, 0, v35, vcc
	global_load_dword v64, v[36:37], off nt
	v_add_co_u32_e32 v36, vcc, 0x36000, v34
	s_nop 1
	v_addc_co_u32_e32 v37, vcc, 0, v35, vcc
	global_load_dword v65, v[36:37], off nt
	v_add_co_u32_e32 v36, vcc, 0x38000, v34
	s_nop 1
	v_addc_co_u32_e32 v37, vcc, 0, v35, vcc
	global_load_dword v66, v[36:37], off nt
	v_add_co_u32_e32 v36, vcc, 0x3a000, v34
	s_nop 1
	v_addc_co_u32_e32 v37, vcc, 0, v35, vcc
	global_load_dword v67, v[36:37], off nt
	v_add_co_u32_e32 v36, vcc, 0x3c000, v34
	s_nop 1
	v_addc_co_u32_e32 v37, vcc, 0, v35, vcc
	v_add_co_u32_e32 v34, vcc, 0x3e000, v34
	global_load_dword v36, v[36:37], off nt
	s_nop 0
	v_addc_co_u32_e32 v35, vcc, 0, v35, vcc
	global_load_dword v34, v[34:35], off nt
	v_add_u32_e32 v35, 0x1c00, v71
	s_waitcnt vmcnt(0)
; #define LAS __attribute__((address_space(3)))
; __device__ __forceinline__ unsigned cvt_pk(float lo, float hi) { f32x2_t v = {lo, hi}; bf16x2_t b = __builtin_convertvector(v, bf16x2_t); return __builtin_bit_cast(unsigned, b); }
; __device__ __forceinline__ unsigned pk_fp8x4(float a, float b, float c, float d) { int w = 0; w = __builtin_amdgcn_cvt_pk_fp8_f32(a, b, w, false); w = __builtin_amdgcn_cvt_pk_fp8_f32(c, d, w, true); return (unsigned)w; }
; template <bool F8 = false>
; __device__ __forceinline__ void p0_transpose_item(const float* W, int K, int N, bf16_t* WT, int k0, int n0, int drow0, const float* gs, LAS float* scr, int lane) {
;     ...
;     for (int i = 0; i < 32; ++i) scr[(2 * i + (lane >> 5)) * 33 + (lane & 31)] = wv[i];
;     asm volatile("s_waitcnt lgkmcnt(0)" ::: "memory");
;     const int c = lane & 7;
; #pragma unroll
;     for (int j = 0; j < 4; ++j) { const int n = (lane >> 3) + 8 * j; const LAS float* s = scr + (8 * c) * 33 + n;
;         if (F8) { u32x2 o8; o8.x = pk_fp8x4(32.f * s[0 * 33], 32.f * s[1 * 33], 32.f * s[2 * 33], 32.f * s[3 * 33]); o8.y = pk_fp8x4(32.f * s[4 * 33], 32.f * s[5 * 33], 32.f * s[6 * 33], 32.f * s[7 * 33]);
;             *(u32x2*)((unsigned char*)WT + (size_t)(drow0 + n) * K + k0 + 8 * c) = o8; }
;         else { u32x4 o; o.x = cvt_pk(s[0 * 33], s[1 * 33]); o.y = cvt_pk(s[2 * 33], s[3 * 33]); o.z = cvt_pk(s[4 * 33], s[5 * 33]); o.w = cvt_pk(s[6 * 33], s[7 * 33]);
;             *(u32x4*)(WT + (size_t)(drow0 + n) * K + k0 + 8 * c) = o; } }
	ds_write2_b32 v71, v38, v39 offset1:66
	ds_write2_b32 v71, v40, v41 offset0:132 offset1:198
	ds_write2_b32 v72, v42, v43 offset0:8 offset1:74
	ds_write2_b32 v72, v44, v45 offset0:140 offset1:206
	ds_write2_b32 v80, v46, v47 offset0:16 offset1:82
	ds_write2_b32 v80, v48, v49 offset0:148 offset1:214
	ds_write2_b32 v82, v50, v51 offset0:24 offset1:90
	ds_write2_b32 v82, v52, v53 offset0:156 offset1:222
	ds_write2_b32 v83, v54, v55 offset0:32 offset1:98
	ds_write2_b32 v83, v56, v57 offset0:164 offset1:230
	ds_write2_b32 v84, v58, v59 offset0:40 offset1:106
	ds_write2_b32 v84, v60, v61 offset0:172 offset1:238
	ds_write2_b32 v85, v62, v63 offset0:48 offset1:114
	ds_write2_b32 v85, v64, v65 offset0:180 offset1:246
	ds_write2_b32 v35, v66, v67 offset0:56 offset1:122
	ds_write2_b32 v35, v36, v34 offset0:188 offset1:254
	s_waitcnt lgkmcnt(0)
	ds_read2_b32 v[40:41], v76 offset0:33 offset1:41
	ds_read2_b32 v[42:43], v76 offset1:8
	ds_read2_b32 v[44:45], v76 offset0:66 offset1:74
	ds_read2_b32 v[46:47], v76 offset0:99 offset1:107
	ds_read2_b32 v[48:49], v76 offset0:132 offset1:140
	ds_read2_b32 v[50:51], v76 offset0:165 offset1:173
	ds_read2_b32 v[52:53], v76 offset0:198 offset1:206
	ds_read2_b32 v[54:55], v76 offset0:231 offset1:239
	v_add_u32_e32 v56, s0, v75
	v_ashrrev_i32_e32 v57, 31, v56
	v_lshl_add_u64 v[38:39], v[10:11], 0, s[68:69]
	v_lshlrev_b64 v[56:57], 11, v[56:57]
	s_waitcnt lgkmcnt(6)
	v_cvt_pk_bf16_f32 v34, v42, v40
	s_waitcnt lgkmcnt(4)
	v_cvt_pk_bf16_f32 v35, v44, v46
	s_waitcnt lgkmcnt(2)
	v_cvt_pk_bf16_f32 v36, v48, v50
	s_waitcnt lgkmcnt(0)
	v_cvt_pk_bf16_f32 v37, v52, v54
	v_lshl_add_u64 v[56:57], v[38:39], 0, v[56:57]
	v_add_u32_e32 v40, s0, v77
	global_store_dwordx4 v[56:57], v[34:37], off nt
	v_add_u32_e32 v56, s0, v78
	v_ashrrev_i32_e32 v57, 31, v56
	v_cvt_pk_bf16_f32 v34, v43, v41
	v_ashrrev_i32_e32 v41, 31, v40
	v_lshlrev_b64 v[40:41], 11, v[40:41]
	v_cvt_pk_bf16_f32 v35, v45, v47
	v_cvt_pk_bf16_f32 v36, v49, v51
	v_cvt_pk_bf16_f32 v37, v53, v55
	v_lshl_add_u64 v[40:41], v[38:39], 0, v[40:41]
	global_store_dwordx4 v[40:41], v[34:37], off nt
	ds_read2_b32 v[40:41], v76 offset0:49 offset1:57
	ds_read2_b32 v[42:43], v76 offset0:16 offset1:24
	ds_read2_b32 v[44:45], v76 offset0:82 offset1:90
	ds_read2_b32 v[46:47], v76 offset0:115 offset1:123
	ds_read2_b32 v[48:49], v76 offset0:148 offset1:156
	ds_read2_b32 v[50:51], v76 offset0:181 offset1:189
	ds_read2_b32 v[52:53], v76 offset0:214 offset1:222
	ds_read2_b32 v[54:55], v76 offset0:247 offset1:255
	v_lshlrev_b64 v[56:57], 11, v[56:57]
	s_waitcnt lgkmcnt(6)
	v_cvt_pk_bf16_f32 v34, v42, v40
	s_waitcnt lgkmcnt(4)
	v_cvt_pk_bf16_f32 v35, v44, v46
	s_waitcnt lgkmcnt(2)
	v_cvt_pk_bf16_f32 v36, v48, v50
	s_waitcnt lgkmcnt(0)
	v_cvt_pk_bf16_f32 v37, v52, v54
	v_lshl_add_u64 v[56:57], v[38:39], 0, v[56:57]
	v_add_u32_e32 v40, s0, v79
	global_store_dwordx4 v[56:57], v[34:37], off nt
	s_nop 1
	v_cvt_pk_bf16_f32 v34, v43, v41
	v_ashrrev_i32_e32 v41, 31, v40
	v_lshlrev_b64 v[40:41], 11, v[40:41]
	v_cvt_pk_bf16_f32 v35, v45, v47
	v_cvt_pk_bf16_f32 v36, v49, v51
	v_cvt_pk_bf16_f32 v37, v53, v55
	v_lshl_add_u64 v[38:39], v[38:39], 0, v[40:41]
	global_store_dwordx4 v[38:39], v[34:37], off nt
	s_waitcnt lgkmcnt(0)

; #define LAS __attribute__((address_space(3)))
; template <bool F8 = false>
; __device__ __forceinline__ void p0_transpose_item(const float* W, int K, int N, bf16_t* WT, int k0, int n0, int drow0, const float* gs, LAS float* scr, int lane) {
;     float wv[32];
; #pragma unroll
;     for (int i = 0; i < 32; ++i) wv[i] = W[(size_t)(k0 + 2 * i + (lane >> 5)) * N + n0 + (lane & 31)];
; template <int PART>
; __device__ __forceinline__ void phase0(const Ptrs& P, LAS float* scr, int gw, int NGW, int lane) {
;     ...
;         if (r < I_SQ) { const int nblk = DM / 32; p0_transpose_item(P.w_brl, DM, DM, (bf16_t*)(ws + WS_WBRL), 64 * (r / nblk), 32 * (r % nblk), 32 * (r % nblk), nullptr, scr, lane); continue; } r -= I_SQ;
;         if (r < I_SQ) { const int nblk = DM / 32; p0_transpose_item(P.w_bra, DM, DM, (bf16_t*)(ws + WS_WBRA), 64 * (r / nblk), 32 * (r % nblk), 32 * (r % nblk), nullptr, scr, lane); continue; } r -= I_SQ;
;         if (r < I_SQ) { const int nblk = DM / 32; p0_transpose_item(P.w_out, DM, DM, (bf16_t*)(ws + WS_WOUT), 64 * (r / nblk), 32 * (r % nblk), 32 * (r % nblk), nullptr, scr, lane); continue; } r -= I_SQ;
.LBB0_440:
	s_andn2_b64 vcc, exec, s[0:1]
	s_cbranch_vccnz .LBB0_442
	s_add_i32 s0, s9, 0x80003000
	s_and_b32 s1, s0, 0x3c0
	s_and_b32 s0, s8, 0x3e0
	v_add_u32_e32 v34, s1, v70
	s_lshl_b32 s68, s0, 2
	v_ashrrev_i32_e32 v35, 31, v34
	v_lshl_add_u64 v[36:37], v[30:31], 0, s[68:69]
	v_lshlrev_b64 v[34:35], 12, v[34:35]
	v_lshl_add_u64 v[34:35], v[36:37], 0, v[34:35]
	v_add_co_u32_e32 v36, vcc, 0x2000, v34
	global_load_dword v38, v[34:35], off nt
	s_nop 0
	v_addc_co_u32_e32 v37, vcc, 0, v35, vcc
	global_load_dword v39, v[36:37], off nt
	v_add_co_u32_e32 v36, vcc, 0x4000, v34
	s_lshl_b32 s68, s1, 1
	s_nop 0
	v_addc_co_u32_e32 v37, vcc, 0, v35, vcc
	global_load_dword v40, v[36:37], off nt
	v_add_co_u32_e32 v36, vcc, 0x6000, v34
	s_nop 1
	v_addc_co_u32_e32 v37, vcc, 0, v35, vcc
	global_load_dword v41, v[36:37], off nt
	v_add_co_u32_e32 v36, vcc, 0x8000, v34
	s_nop 1
	v_addc_co_u32_e32 v37, vcc, 0, v35, vcc
	global_load_dword v42, v[36:37], off nt
	v_add_co_u32_e32 v36, vcc, 0xa000, v34
	s_nop 1
	v_addc_co_u32_e32 v37, vcc, 0, v35, vcc
	global_load_dword v43, v[36:37], off nt
	v_add_co_u32_e32 v36, vcc, 0xc000, v34
	s_nop 1
	v_addc_co_u32_e32 v37, vcc, 0, v35, vcc
	global_load_dword v44, v[36:37], off nt
	v_add_co_u32_e32 v36, vcc, 0xe000, v34
	s_nop 1
	v_addc_co_u32_e32 v37, vcc, 0, v35, vcc
	global_load_dword v45, v[36:37], off nt
	v_add_co_u32_e32 v36, vcc, 0x10000, v34
	s_nop 1
	v_addc_co_u32_e32 v37, vcc, 0, v35, vcc
	global_load_dword v46, v[36:37], off nt
	v_add_co_u32_e32 v36, vcc, 0x12000, v34
	s_nop 1
	v_addc_co_u32_e32 v37, vcc, 0, v35, vcc
	global_load_dword v47, v[36:37], off nt
	v_add_co_u32_e32 v36, vcc, 0x14000, v34
	s_nop 1
	v_addc_co_u32_e32 v37, vcc, 0, v35, vcc
	global_load_dword v48, v[36:37], off nt
	v_add_co_u32_e32 v36, vcc, 0x16000, v34
	s_nop 1
	v_addc_co_u32_e32 v37, vcc, 0, v35, vcc
	global_load_dword v49, v[36:37], off nt
	v_add_co_u32_e32 v36, vcc, 0x18000, v34
	s_nop 1
	v_addc_co_u32_e32 v37, vcc, 0, v35, vcc
	global_load_dword v50, v[36:37], off nt
	v_add_co_u32_e32 v36, vcc, 0x1a000, v34
	s_nop 1
	v_addc_co_u32_e32 v37, vcc, 0, v35, vcc
	global_load_dword v51, v[36:37], off nt
	v_add_co_u32_e32 v36, vcc, 0x1c000, v34
	s_nop 1
	v_addc_co_u32_e32 v37, vcc, 0, v35, vcc
	global_load_dword v52, v[36:37], off nt
	v_add_co_u32_e32 v36, vcc, 0x1e000, v34
	s_nop 1
	v_addc_co_u32_e32 v37, vcc, 0, v35, vcc
	global_load_dword v53, v[36:37], off nt
	v_add_co_u32_e32 v36, vcc, 0x20000, v34
	s_nop 1
	v_addc_co_u32_e32 v37, vcc, 0, v35, vcc
	global_load_dword v54, v[36:37], off nt
	v_add_co_u32_e32 v36, vcc, 0x22000, v34
	s_nop 1
	v_addc_co_u32_e32 v37, vcc, 0, v35, vcc
	global_load_dword v55, v[36:37], off nt
	v_add_co_u32_e32 v36, vcc, 0x24000, v34
	s_nop 1
	v_addc_co_u32_e32 v37, vcc, 0, v35, vcc
	global_load_dword v56, v[36:37], off nt
	v_add_co_u32_e32 v36, vcc, 0x26000, v34
	s_nop 1
	v_addc_co_u32_e32 v37, vcc, 0, v35, vcc
	global_load_dword v57, v[36:37], off nt
	v_add_co_u32_e32 v36, vcc, 0x28000, v34
	s_nop 1
	v_addc_co_u32_e32 v37, vcc, 0, v35, vcc
	global_load_dword v58, v[36:37], off nt
	v_add_co_u32_e32 v36, vcc, 0x2a000, v34
	s_nop 1
	v_addc_co_u32_e32 v37, vcc, 0, v35, vcc
	global_load_dword v59, v[36:37], off nt
	v_add_co_u32_e32 v36, vcc, 0x2c000, v34
	s_nop 1
	v_addc_co_u32_e32 v37, vcc, 0, v35, vcc
	global_load_dword v60, v[36:37], off nt
	v_add_co_u32_e32 v36, vcc, 0x2e000, v34
	s_nop 1
	v_addc_co_u32_e32 v37, vcc, 0, v35, vcc
	global_load_dword v61, v[36:37], off nt
	v_add_co_u32_e32 v36, vcc, 0x30000, v34
	s_nop 1
	v_addc_co_u32_e32 v37, vcc, 0, v35, vcc
	global_load_dword v62, v[36:37], off nt
	v_add_co_u32_e32 v36, vcc, 0x32000, v34
	s_nop 1
	v_addc_co_u32_e32 v37, vcc, 0, v35, vcc
	global_load_dword v63, v[36:37], off nt
	v_add_co_u32_e32 v36, vcc, 0x34000, v34
	s_nop 1
	v_addc_co_u32_e32 v37, vcc, 0, v35, vcc
	global_load_dword v64, v[36:37], off nt
	v_add_co_u32_e32 v36, vcc, 0x36000, v34
	s_nop 1
	v_addc_co_u32_e32 v37, vcc, 0, v35, vcc
	global_load_dword v65, v[36:37], off nt
	v_add_co_u32_e32 v36, vcc, 0x38000, v34
	s_nop 1
	v_addc_co_u32_e32 v37, vcc, 0, v35, vcc
	global_load_dword v66, v[36:37], off nt
	v_add_co_u32_e32 v36, vcc, 0x3a000, v34
	s_nop 1
	v_addc_co_u32_e32 v37, vcc, 0, v35, vcc
	global_load_dword v67, v[36:37], off nt
	v_add_co_u32_e32 v36, vcc, 0x3c000, v34
	s_nop 1
	v_addc_co_u32_e32 v37, vcc, 0, v35, vcc
	v_add_co_u32_e32 v34, vcc, 0x3e000, v34
	global_load_dword v36, v[36:37], off nt
	s_nop 0
	v_addc_co_u32_e32 v35, vcc, 0, v35, vcc
	global_load_dword v34, v[34:35], off nt
	v_add_u32_e32 v35, 0x1c00, v71
	s_waitcnt vmcnt(0)
; #define LAS __attribute__((address_space(3)))
; __device__ __forceinline__ unsigned cvt_pk(float lo, float hi) { f32x2_t v = {lo, hi}; bf16x2_t b = __builtin_convertvector(v, bf16x2_t); return __builtin_bit_cast(unsigned, b); }
; __device__ __forceinline__ unsigned pk_fp8x4(float a, float b, float c, float d) { int w = 0; w = __builtin_amdgcn_cvt_pk_fp8_f32(a, b, w, false); w = __builtin_amdgcn_cvt_pk_fp8_f32(c, d, w, true); return (unsigned)w; }
; template <bool F8 = false>
; __device__ __forceinline__ void p0_transpose_item(const float* W, int K, int N, bf16_t* WT, int k0, int n0, int drow0, const float* gs, LAS float* scr, int lane) {
;     ...
;     for (int i = 0; i < 32; ++i) scr[(2 * i + (lane >> 5)) * 33 + (lane & 31)] = wv[i];
;     asm volatile("s_waitcnt lgkmcnt(0)" ::: "memory");
;     const int c = lane & 7;
; #pragma unroll
;     for (int j = 0; j < 4; ++j) { const int n = (lane >> 3) + 8 * j; const LAS float* s = scr + (8 * c) * 33 + n;
;         if (F8) { u32x2 o8; o8.x = pk_fp8x4(32.f * s[0 * 33], 32.f * s[1 * 33], 32.f * s[2 * 33], 32.f * s[3 * 33]); o8.y = pk_fp8x4(32.f * s[4 * 33], 32.f * s[5 * 33], 32.f * s[6 * 33], 32.f * s[7 * 33]);
;             *(u32x2*)((unsigned char*)WT + (size_t)(drow0 + n) * K + k0 + 8 * c) = o8; }
;         else { u32x4 o; o.x = cvt_pk(s[0 * 33], s[1 * 33]); o.y = cvt_pk(s[2 * 33], s[3 * 33]); o.z = cvt_pk(s[4 * 33], s[5 * 33]); o.w = cvt_pk(s[6 * 33], s[7 * 33]);
;             *(u32x4*)(WT + (size_t)(drow0 + n) * K + k0 + 8 * c) = o; } }
	ds_write2_b32 v71, v38, v39 offset1:66
	ds_write2_b32 v71, v40, v41 offset0:132 offset1:198
	ds_write2_b32 v72, v42, v43 offset0:8 offset1:74
	ds_write2_b32 v72, v44, v45 offset0:140 offset1:206
	ds_write2_b32 v80, v46, v47 offset0:16 offset1:82
	ds_write2_b32 v80, v48, v49 offset0:148 offset1:214
	ds_write2_b32 v82, v50, v51 offset0:24 offset1:90
	ds_write2_b32 v82, v52, v53 offset0:156 offset1:222
	ds_write2_b32 v83, v54, v55 offset0:32 offset1:98
	ds_write2_b32 v83, v56, v57 offset0:164 offset1:230
	ds_write2_b32 v84, v58, v59 offset0:40 offset1:106
	ds_write2_b32 v84, v60, v61 offset0:172 offset1:238
	ds_write2_b32 v85, v62, v63 offset0:48 offset1:114
	ds_write2_b32 v85, v64, v65 offset0:180 offset1:246
	ds_write2_b32 v35, v66, v67 offset0:56 offset1:122
	ds_write2_b32 v35, v36, v34 offset0:188 offset1:254
	s_waitcnt lgkmcnt(0)
	ds_read2_b32 v[40:41], v76 offset0:33 offset1:41
	ds_read2_b32 v[42:43], v76 offset1:8
	ds_read2_b32 v[44:45], v76 offset0:66 offset1:74
	ds_read2_b32 v[46:47], v76 offset0:99 offset1:107
	ds_read2_b32 v[48:49], v76 offset0:132 offset1:140
	ds_read2_b32 v[50:51], v76 offset0:165 offset1:173
	ds_read2_b32 v[52:53], v76 offset0:198 offset1:206
	ds_read2_b32 v[54:55], v76 offset0:231 offset1:239
	v_add_u32_e32 v56, s0, v75
	v_ashrrev_i32_e32 v57, 31, v56
	v_lshl_add_u64 v[38:39], v[12:13], 0, s[68:69]
	v_lshlrev_b64 v[56:57], 11, v[56:57]
	s_waitcnt lgkmcnt(6)
	v_cvt_pk_bf16_f32 v34, v42, v40
	s_waitcnt lgkmcnt(4)
	v_cvt_pk_bf16_f32 v35, v44, v46
	s_waitcnt lgkmcnt(2)
	v_cvt_pk_bf16_f32 v36, v48, v50
	s_waitcnt lgkmcnt(0)
	v_cvt_pk_bf16_f32 v37, v52, v54
	v_lshl_add_u64 v[56:57], v[38:39], 0, v[56:57]
	v_add_u32_e32 v40, s0, v77
	global_store_dwordx4 v[56:57], v[34:37], off nt
	v_add_u32_e32 v56, s0, v78
	v_ashrrev_i32_e32 v57, 31, v56
	v_cvt_pk_bf16_f32 v34, v43, v41
	v_ashrrev_i32_e32 v41, 31, v40
	v_lshlrev_b64 v[40:41], 11, v[40:41]
	v_cvt_pk_bf16_f32 v35, v45, v47
	v_cvt_pk_bf16_f32 v36, v49, v51
	v_cvt_pk_bf16_f32 v37, v53, v55
	v_lshl_add_u64 v[40:41], v[38:39], 0, v[40:41]
	global_store_dwordx4 v[40:41], v[34:37], off nt
	ds_read2_b32 v[40:41], v76 offset0:49 offset1:57
	ds_read2_b32 v[42:43], v76 offset0:16 offset1:24
	ds_read2_b32 v[44:45], v76 offset0:82 offset1:90
	ds_read2_b32 v[46:47], v76 offset0:115 offset1:123
	ds_read2_b32 v[48:49], v76 offset0:148 offset1:156
	ds_read2_b32 v[50:51], v76 offset0:181 offset1:189
	ds_read2_b32 v[52:53], v76 offset0:214 offset1:222
	ds_read2_b32 v[54:55], v76 offset0:247 offset1:255
	v_lshlrev_b64 v[56:57], 11, v[56:57]
	s_waitcnt lgkmcnt(6)
	v_cvt_pk_bf16_f32 v34, v42, v40
	s_waitcnt lgkmcnt(4)
	v_cvt_pk_bf16_f32 v35, v44, v46
	s_waitcnt lgkmcnt(2)
	v_cvt_pk_bf16_f32 v36, v48, v50
	s_waitcnt lgkmcnt(0)
	v_cvt_pk_bf16_f32 v37, v52, v54
	v_lshl_add_u64 v[56:57], v[38:39], 0, v[56:57]
	v_add_u32_e32 v40, s0, v79
	global_store_dwordx4 v[56:57], v[34:37], off nt
	s_nop 1
	v_cvt_pk_bf16_f32 v34, v43, v41
	v_ashrrev_i32_e32 v41, 31, v40
	v_lshlrev_b64 v[40:41], 11, v[40:41]
	v_cvt_pk_bf16_f32 v35, v45, v47
	v_cvt_pk_bf16_f32 v36, v49, v51
	v_cvt_pk_bf16_f32 v37, v53, v55
	v_lshl_add_u64 v[38:39], v[38:39], 0, v[40:41]
	global_store_dwordx4 v[38:39], v[34:37], off nt
	s_waitcnt lgkmcnt(0)

; template <bool F8 = false>
; __device__ __forceinline__ void p0_transpose_item(const float* W, int K, int N, bf16_t* WT, int k0, int n0, int drow0, const float* gs, LAS float* scr, int lane) {
;     ...
;     for (int i = 0; i < 32; ++i) wv[i] = W[(size_t)(k0 + 2 * i + (lane >> 5)) * N + n0 + (lane & 31)];
;     if (gs) {
; #pragma unroll
;         for (int i = 0; i < 32; ++i) wv[i] *= gs[k0 + 2 * i + (lane >> 5)]; }
; #pragma unroll
;     for (int i = 0; i < 32; ++i) scr[(2 * i + (lane >> 5)) * 33 + (lane & 31)] = wv[i];
; template <int PART>
; __device__ __forceinline__ void phase0(const Ptrs& P, LAS float* scr, int gw, int NGW, int lane) {
;     ...
;         if (r < I_IN) { const int nblk = NIN / 32, kb = r / nblk, nb = r % nblk, n0 = 32 * nb, sec = n0 >> 10;
;             if (sec < 5) p0_transpose_item(P.w_in, DM, NIN, (bf16_t*)(ws + WS_WIN), 64 * kb, n0, n0, nullptr, scr, lane);
;             else p0_transpose_item<true>(P.w_in, DM, NIN, (bf16_t*)(ws + WS_WG8), 64 * kb, n0, n0 - 5120, nullptr, scr, lane);
.LBB0_443:
	s_andn2_b64 vcc, exec, s[0:1]
	s_cbranch_vccnz .LBB0_412
	s_add_i32 s0, s24, 0xe00
	s_mul_hi_i32 s1, s0, 0x92492493
	s_add_i32 s1, s1, s0
	s_lshr_b32 s2, s1, 31
	s_ashr_i32 s1, s1, 7
	s_add_i32 s1, s1, s2
	s_mul_i32 s2, s1, 0xe0
	s_sub_i32 s2, s0, s2
	s_lshl_b32 s4, s1, 6
	s_lshl_b32 s0, s2, 5
	v_add_u32_e32 v66, s4, v70
	s_cmpk_gt_i32 s2, 0x9f
	s_mov_b64 s[6:7], -1
	v_add_u32_e32 v65, 2, v66
	v_add_u32_e32 v64, 4, v66
	v_add_u32_e32 v63, 6, v66
	v_add_u32_e32 v62, 8, v66
	v_add_u32_e32 v61, 10, v66
	v_add_u32_e32 v60, 12, v66
	v_add_u32_e32 v59, 14, v66
	v_add_u32_e32 v58, 16, v66
	v_add_u32_e32 v57, 18, v66
	v_add_u32_e32 v56, 20, v66
	v_add_u32_e32 v55, 22, v66
	v_add_u32_e32 v54, 24, v66
	v_add_u32_e32 v53, 26, v66
	v_add_u32_e32 v52, 28, v66
	v_add_u32_e32 v51, 30, v66
	v_add_u32_e32 v50, 32, v66
	v_add_u32_e32 v49, 34, v66
	v_add_u32_e32 v48, 36, v66
	v_add_u32_e32 v47, 38, v66
	v_add_u32_e32 v46, 40, v66
	v_add_u32_e32 v45, 42, v66
	v_add_u32_e32 v44, 44, v66
	v_add_u32_e32 v43, 46, v66
	v_add_u32_e32 v42, 48, v66
	v_add_u32_e32 v41, 50, v66
	v_add_u32_e32 v40, 52, v66
	v_add_u32_e32 v39, 54, v66
	v_add_u32_e32 v38, 56, v66
	v_add_u32_e32 v37, 58, v66
	v_add_u32_e32 v36, 60, v66
	v_add_u32_e32 v35, 62, v66
	v_add_u32_e32 v34, 0x1c00, v71
	s_cbranch_scc0 .LBB0_446
	s_mov_b32 s1, s69
	v_lshl_add_u64 v[68:69], s[0:1], 2, v[32:33]
	v_mad_i64_i32 v[86:87], s[2:3], v66, s29, v[68:69]
	global_load_dword v67, v[86:87], off nt
	v_mad_i64_i32 v[86:87], s[2:3], v65, s29, v[68:69]
	global_load_dword v88, v[86:87], off nt
	v_mad_i64_i32 v[86:87], s[2:3], v64, s29, v[68:69]
	global_load_dword v89, v[86:87], off nt
	v_mad_i64_i32 v[86:87], s[2:3], v63, s29, v[68:69]
	global_load_dword v90, v[86:87], off nt
	v_mad_i64_i32 v[86:87], s[2:3], v62, s29, v[68:69]
	global_load_dword v91, v[86:87], off nt
	v_mad_i64_i32 v[86:87], s[2:3], v61, s29, v[68:69]
	global_load_dword v92, v[86:87], off nt
	v_mad_i64_i32 v[86:87], s[2:3], v60, s29, v[68:69]
	global_load_dword v93, v[86:87], off nt
	v_mad_i64_i32 v[86:87], s[2:3], v59, s29, v[68:69]
	global_load_dword v94, v[86:87], off nt
	v_mad_i64_i32 v[86:87], s[2:3], v58, s29, v[68:69]
	global_load_dword v95, v[86:87], off nt
	v_mad_i64_i32 v[86:87], s[2:3], v57, s29, v[68:69]
	global_load_dword v96, v[86:87], off nt
	v_mad_i64_i32 v[86:87], s[2:3], v56, s29, v[68:69]
	global_load_dword v97, v[86:87], off nt
	v_mad_i64_i32 v[86:87], s[2:3], v55, s29, v[68:69]
	global_load_dword v98, v[86:87], off nt
	v_mad_i64_i32 v[86:87], s[2:3], v54, s29, v[68:69]
	global_load_dword v99, v[86:87], off nt
	v_mad_i64_i32 v[86:87], s[2:3], v53, s29, v[68:69]
	global_load_dword v100, v[86:87], off nt
	v_mad_i64_i32 v[86:87], s[2:3], v52, s29, v[68:69]
	global_load_dword v101, v[86:87], off nt
	v_mad_i64_i32 v[86:87], s[2:3], v51, s29, v[68:69]
	global_load_dword v102, v[86:87], off nt
	v_mad_i64_i32 v[86:87], s[2:3], v50, s29, v[68:69]
	global_load_dword v103, v[86:87], off nt
	v_mad_i64_i32 v[86:87], s[2:3], v49, s29, v[68:69]
	global_load_dword v104, v[86:87], off nt
	v_mad_i64_i32 v[86:87], s[2:3], v48, s29, v[68:69]
	global_load_dword v105, v[86:87], off nt
	v_mad_i64_i32 v[86:87], s[2:3], v47, s29, v[68:69]
	global_load_dword v106, v[86:87], off nt
	v_mad_i64_i32 v[86:87], s[2:3], v46, s29, v[68:69]
	global_load_dword v107, v[86:87], off nt
	v_mad_i64_i32 v[86:87], s[2:3], v45, s29, v[68:69]
	global_load_dword v108, v[86:87], off nt
	v_mad_i64_i32 v[86:87], s[2:3], v44, s29, v[68:69]
	global_load_dword v109, v[86:87], off nt
	v_mad_i64_i32 v[86:87], s[2:3], v43, s29, v[68:69]
	global_load_dword v110, v[86:87], off nt
	v_mad_i64_i32 v[86:87], s[2:3], v42, s29, v[68:69]
	global_load_dword v111, v[86:87], off nt
	v_mad_i64_i32 v[86:87], s[2:3], v41, s29, v[68:69]
	global_load_dword v112, v[86:87], off nt
	v_mad_i64_i32 v[86:87], s[2:3], v40, s29, v[68:69]
	global_load_dword v113, v[86:87], off nt
	v_mad_i64_i32 v[86:87], s[2:3], v39, s29, v[68:69]
	global_load_dword v114, v[86:87], off nt
	v_mad_i64_i32 v[86:87], s[2:3], v38, s29, v[68:69]
	global_load_dword v115, v[86:87], off nt
	v_mad_i64_i32 v[86:87], s[2:3], v37, s29, v[68:69]
	global_load_dword v116, v[86:87], off nt
	v_mad_i64_i32 v[86:87], s[2:3], v36, s29, v[68:69]
	v_mad_i64_i32 v[68:69], s[2:3], v35, s29, v[68:69]
	global_load_dword v86, v[86:87], off nt
	s_add_i32 s1, s0, 0xffffec00
	global_load_dword v68, v[68:69], off nt
	s_waitcnt vmcnt(0)
	ds_write2_b32 v71, v67, v88 offset1:66
	ds_write2_b32 v71, v89, v90 offset0:132 offset1:198
	ds_write2_b32 v72, v91, v92 offset0:8 offset1:74
	ds_write2_b32 v72, v93, v94 offset0:140 offset1:206
	ds_write2_b32 v80, v95, v96 offset0:16 offset1:82
	ds_write2_b32 v80, v97, v98 offset0:148 offset1:214
	ds_write2_b32 v82, v99, v100 offset0:24 offset1:90
	ds_write2_b32 v82, v101, v102 offset0:156 offset1:222
	ds_write2_b32 v83, v103, v104 offset0:32 offset1:98
	ds_write2_b32 v83, v105, v106 offset0:164 offset1:230
	ds_write2_b32 v84, v107, v108 offset0:40 offset1:106
	ds_write2_b32 v84, v109, v110 offset0:172 offset1:238
	ds_write2_b32 v85, v111, v112 offset0:48 offset1:114
	ds_write2_b32 v85, v113, v114 offset0:180 offset1:246
	ds_write2_b32 v34, v115, v116 offset0:56 offset1:122
	ds_write2_b32 v34, v86, v68 offset0:188 offset1:254
	s_waitcnt lgkmcnt(0)
	ds_read2_b32 v[68:69], v76 offset1:8
	ds_read2_b32 v[86:87], v76 offset0:33 offset1:41
	ds_read2_b32 v[88:89], v76 offset0:66 offset1:74
	ds_read2_b32 v[92:93], v76 offset0:99 offset1:107
	ds_read2_b32 v[94:95], v76 offset0:132 offset1:140
	ds_read2_b32 v[96:97], v76 offset0:165 offset1:173
	v_mov_b32_e32 v98, v73
	s_waitcnt lgkmcnt(5)
; #define LAS __attribute__((address_space(3)))
; __device__ __forceinline__ unsigned pk_fp8x4(float a, float b, float c, float d) { int w = 0; w = __builtin_amdgcn_cvt_pk_fp8_f32(a, b, w, false); w = __builtin_amdgcn_cvt_pk_fp8_f32(c, d, w, true); return (unsigned)w; }
; template <bool F8 = false>
; __device__ __forceinline__ void p0_transpose_item(const float* W, int K, int N, bf16_t* WT, int k0, int n0, int drow0, const float* gs, LAS float* scr, int lane) {
;     ...
;     for (int j = 0; j < 4; ++j) { const int n = (lane >> 3) + 8 * j; const LAS float* s = scr + (8 * c) * 33 + n;
;         if (F8) { u32x2 o8; o8.x = pk_fp8x4(32.f * s[0 * 33], 32.f * s[1 * 33], 32.f * s[2 * 33], 32.f * s[3 * 33]); o8.y = pk_fp8x4(32.f * s[4 * 33], 32.f * s[5 * 33], 32.f * s[6 * 33], 32.f * s[7 * 33]);
;             *(u32x2*)((unsigned char*)WT + (size_t)(drow0 + n) * K + k0 + 8 * c) = o8; }
	v_mul_f32_e32 v67, 0x42000000, v68
	s_waitcnt lgkmcnt(4)
	v_mul_f32_e32 v68, 0x42000000, v86
	ds_read2_b32 v[100:101], v76 offset0:198 offset1:206
	ds_read2_b32 v[102:103], v76 offset0:231 offset1:239
	v_cvt_pk_fp8_f32 v98, v67, v68
	s_waitcnt lgkmcnt(3)
	v_mul_f32_e32 v67, 0x42000000, v94
	s_waitcnt lgkmcnt(2)
	v_mul_f32_e32 v68, 0x42000000, v96
	v_mov_b32_e32 v99, v73
	v_cvt_pk_fp8_f32 v99, v67, v68
	s_waitcnt lgkmcnt(1)
	v_mul_f32_e32 v67, 0x42000000, v100
	s_waitcnt lgkmcnt(0)
	v_mul_f32_e32 v68, 0x42000000, v102
	v_mul_f32_e32 v86, 0x42000000, v88
	v_mul_f32_e32 v88, 0x42000000, v92
	v_cvt_pk_fp8_f32 v99, v67, v68 op_sel:[0,0,1]
	v_mul_f32_e32 v67, 0x42000000, v69
	v_mul_f32_e32 v69, 0x42000000, v87
	v_mov_b32_e32 v68, v73
	v_cvt_pk_fp8_f32 v98, v86, v88 op_sel:[0,0,1]
	v_cvt_pk_fp8_f32 v68, v67, v69
	v_mul_f32_e32 v67, 0x42000000, v95
	v_mul_f32_e32 v88, 0x42000000, v97
	v_mov_b32_e32 v69, v73
	v_cvt_pk_fp8_f32 v69, v67, v88
	v_mul_f32_e32 v86, 0x42000000, v89
	v_mul_f32_e32 v87, 0x42000000, v93
	v_add_u32_e32 v104, s1, v75
	v_cvt_pk_fp8_f32 v68, v86, v87 op_sel:[0,0,1]
	v_mul_f32_e32 v67, 0x42000000, v101
	v_mul_f32_e32 v86, 0x42000000, v103
	s_ashr_i32 s5, s4, 31
	v_ashrrev_i32_e32 v105, 31, v104
	v_cvt_pk_fp8_f32 v69, v67, v86 op_sel:[0,0,1]
	v_add_u32_e32 v86, s1, v77
	v_lshl_add_u64 v[90:91], v[14:15], 0, s[4:5]
	v_lshlrev_b64 v[104:105], 10, v[104:105]
	v_ashrrev_i32_e32 v87, 31, v86
	v_lshl_add_u64 v[104:105], v[90:91], 0, v[104:105]
	v_lshlrev_b64 v[86:87], 10, v[86:87]
	global_store_dwordx2 v[104:105], v[98:99], off nt
	v_lshl_add_u64 v[86:87], v[90:91], 0, v[86:87]
	ds_read2_b32 v[88:89], v76 offset0:16 offset1:24
	ds_read2_b32 v[92:93], v76 offset0:49 offset1:57
	ds_read2_b32 v[94:95], v76 offset0:82 offset1:90
	global_store_dwordx2 v[86:87], v[68:69], off nt
	ds_read2_b32 v[68:69], v76 offset0:115 offset1:123
	ds_read2_b32 v[86:87], v76 offset0:148 offset1:156
	ds_read2_b32 v[96:97], v76 offset0:181 offset1:189
	s_waitcnt lgkmcnt(5)
	v_mul_f32_e32 v67, 0x42000000, v88
	s_waitcnt lgkmcnt(4)
	v_mul_f32_e32 v88, 0x42000000, v92
	v_mov_b32_e32 v98, v73
	ds_read2_b32 v[100:101], v76 offset0:214 offset1:222
	ds_read2_b32 v[102:103], v76 offset0:247 offset1:255
	v_cvt_pk_fp8_f32 v98, v67, v88
	s_waitcnt lgkmcnt(3)
	v_mul_f32_e32 v67, 0x42000000, v86
	s_waitcnt lgkmcnt(2)
	v_mul_f32_e32 v86, 0x42000000, v96
	v_mov_b32_e32 v99, v73
	v_cvt_pk_fp8_f32 v99, v67, v86
	v_mul_f32_e32 v92, 0x42000000, v94
	v_mul_f32_e32 v68, 0x42000000, v68
	v_cvt_pk_fp8_f32 v98, v92, v68 op_sel:[0,0,1]
	s_waitcnt lgkmcnt(1)
	v_mul_f32_e32 v67, 0x42000000, v100
	s_waitcnt lgkmcnt(0)
	v_mul_f32_e32 v68, 0x42000000, v102
	v_cvt_pk_fp8_f32 v99, v67, v68 op_sel:[0,0,1]
	v_mul_f32_e32 v67, 0x42000000, v89
	v_mul_f32_e32 v86, 0x42000000, v93
	v_mov_b32_e32 v68, v73
	v_mul_f32_e32 v89, 0x42000000, v69
	v_cvt_pk_fp8_f32 v68, v67, v86
	v_mul_f32_e32 v67, 0x42000000, v87
	v_mul_f32_e32 v86, 0x42000000, v97
	v_mov_b32_e32 v69, v73
	v_cvt_pk_fp8_f32 v69, v67, v86
	v_mul_f32_e32 v88, 0x42000000, v95
	v_mul_f32_e32 v67, 0x42000000, v101
	v_mul_f32_e32 v86, 0x42000000, v103
	v_add_u32_e32 v104, s1, v78
	v_cvt_pk_fp8_f32 v68, v88, v89 op_sel:[0,0,1]
	v_cvt_pk_fp8_f32 v69, v67, v86 op_sel:[0,0,1]
	v_add_u32_e32 v86, s1, v79
	v_ashrrev_i32_e32 v105, 31, v104
	v_ashrrev_i32_e32 v87, 31, v86
	v_lshlrev_b64 v[104:105], 10, v[104:105]
	v_lshlrev_b64 v[86:87], 10, v[86:87]
	v_lshl_add_u64 v[104:105], v[90:91], 0, v[104:105]
	v_lshl_add_u64 v[86:87], v[90:91], 0, v[86:87]
	global_store_dwordx2 v[104:105], v[98:99], off nt
	global_store_dwordx2 v[86:87], v[68:69], off nt
	s_waitcnt lgkmcnt(0)
	s_mov_b64 s[6:7], 0
; #define LAS __attribute__((address_space(3)))
; __device__ __forceinline__ unsigned cvt_pk(float lo, float hi) { f32x2_t v = {lo, hi}; bf16x2_t b = __builtin_convertvector(v, bf16x2_t); return __builtin_bit_cast(unsigned, b); }
; __device__ __forceinline__ unsigned pk_fp8x4(float a, float b, float c, float d) { int w = 0; w = __builtin_amdgcn_cvt_pk_fp8_f32(a, b, w, false); w = __builtin_amdgcn_cvt_pk_fp8_f32(c, d, w, true); return (unsigned)w; }
; template <bool F8 = false>
; __device__ __forceinline__ void p0_transpose_item(const float* W, int K, int N, bf16_t* WT, int k0, int n0, int drow0, const float* gs, LAS float* scr, int lane) {
;     ...
;     for (int i = 0; i < 32; ++i) wv[i] = W[(size_t)(k0 + 2 * i + (lane >> 5)) * N + n0 + (lane & 31)];
;     if (gs) {
; #pragma unroll
;         for (int i = 0; i < 32; ++i) wv[i] *= gs[k0 + 2 * i + (lane >> 5)]; }
; #pragma unroll
;     for (int i = 0; i < 32; ++i) scr[(2 * i + (lane >> 5)) * 33 + (lane & 31)] = wv[i];
;     asm volatile("s_waitcnt lgkmcnt(0)" ::: "memory");
;     const int c = lane & 7;
; #pragma unroll
;     for (int j = 0; j < 4; ++j) { const int n = (lane >> 3) + 8 * j; const LAS float* s = scr + (8 * c) * 33 + n;
;         if (F8) { u32x2 o8; o8.x = pk_fp8x4(32.f * s[0 * 33], 32.f * s[1 * 33], 32.f * s[2 * 33], 32.f * s[3 * 33]); o8.y = pk_fp8x4(32.f * s[4 * 33], 32.f * s[5 * 33], 32.f * s[6 * 33], 32.f * s[7 * 33]);
;             *(u32x2*)((unsigned char*)WT + (size_t)(drow0 + n) * K + k0 + 8 * c) = o8; }
;         else { u32x4 o; o.x = cvt_pk(s[0 * 33], s[1 * 33]); o.y = cvt_pk(s[2 * 33], s[3 * 33]); o.z = cvt_pk(s[4 * 33], s[5 * 33]); o.w = cvt_pk(s[6 * 33], s[7 * 33]);
;             *(u32x4*)(WT + (size_t)(drow0 + n) * K + k0 + 8 * c) = o; } }
.LBB0_446:
	s_andn2_b64 vcc, exec, s[6:7]
	s_cbranch_vccnz .LBB0_412
	s_ashr_i32 s1, s0, 31
	v_lshl_add_u64 v[68:69], s[0:1], 2, v[32:33]
	v_mad_i64_i32 v[66:67], s[2:3], v66, s29, v[68:69]
	global_load_dword v86, v[66:67], off nt
	v_mad_i64_i32 v[66:67], s[2:3], v65, s29, v[68:69]
	v_mad_i64_i32 v[64:65], s[2:3], v64, s29, v[68:69]
	global_load_dword v66, v[66:67], off nt
	s_ashr_i32 s5, s4, 31
	global_load_dword v67, v[64:65], off nt
	v_mad_i64_i32 v[64:65], s[2:3], v63, s29, v[68:69]
	v_mad_i64_i32 v[62:63], s[2:3], v62, s29, v[68:69]
	global_load_dword v64, v[64:65], off nt
	s_nop 0
	global_load_dword v65, v[62:63], off nt
	v_mad_i64_i32 v[62:63], s[2:3], v61, s29, v[68:69]
	v_mad_i64_i32 v[60:61], s[2:3], v60, s29, v[68:69]
	global_load_dword v62, v[62:63], off nt
	s_nop 0
	global_load_dword v63, v[60:61], off nt
	v_mad_i64_i32 v[60:61], s[2:3], v59, s29, v[68:69]
	v_mad_i64_i32 v[58:59], s[2:3], v58, s29, v[68:69]
	global_load_dword v60, v[60:61], off nt
	s_nop 0
	global_load_dword v61, v[58:59], off nt
	v_mad_i64_i32 v[58:59], s[2:3], v57, s29, v[68:69]
	v_mad_i64_i32 v[56:57], s[2:3], v56, s29, v[68:69]
	global_load_dword v58, v[58:59], off nt
	s_nop 0
	global_load_dword v59, v[56:57], off nt
	v_mad_i64_i32 v[56:57], s[2:3], v55, s29, v[68:69]
	v_mad_i64_i32 v[54:55], s[2:3], v54, s29, v[68:69]
	global_load_dword v56, v[56:57], off nt
	s_nop 0
	global_load_dword v57, v[54:55], off nt
	v_mad_i64_i32 v[54:55], s[2:3], v53, s29, v[68:69]
	v_mad_i64_i32 v[52:53], s[2:3], v52, s29, v[68:69]
	global_load_dword v54, v[54:55], off nt
	s_nop 0
	global_load_dword v55, v[52:53], off nt
	v_mad_i64_i32 v[52:53], s[2:3], v51, s29, v[68:69]
	v_mad_i64_i32 v[50:51], s[2:3], v50, s29, v[68:69]
	global_load_dword v52, v[52:53], off nt
	s_nop 0
	global_load_dword v53, v[50:51], off nt
	v_mad_i64_i32 v[50:51], s[2:3], v49, s29, v[68:69]
	v_mad_i64_i32 v[48:49], s[2:3], v48, s29, v[68:69]
	global_load_dword v50, v[50:51], off nt
	s_nop 0
	global_load_dword v51, v[48:49], off nt
	v_mad_i64_i32 v[48:49], s[2:3], v47, s29, v[68:69]
	v_mad_i64_i32 v[46:47], s[2:3], v46, s29, v[68:69]
	global_load_dword v48, v[48:49], off nt
	s_nop 0
	global_load_dword v49, v[46:47], off nt
	v_mad_i64_i32 v[46:47], s[2:3], v45, s29, v[68:69]
	v_mad_i64_i32 v[44:45], s[2:3], v44, s29, v[68:69]
	global_load_dword v46, v[46:47], off nt
	s_nop 0
	global_load_dword v47, v[44:45], off nt
	v_mad_i64_i32 v[44:45], s[2:3], v43, s29, v[68:69]
	v_mad_i64_i32 v[42:43], s[2:3], v42, s29, v[68:69]
	global_load_dword v44, v[44:45], off nt
	s_nop 0
	global_load_dword v45, v[42:43], off nt
	v_mad_i64_i32 v[42:43], s[2:3], v41, s29, v[68:69]
	v_mad_i64_i32 v[40:41], s[2:3], v40, s29, v[68:69]
	global_load_dword v42, v[42:43], off nt
	s_nop 0
	global_load_dword v43, v[40:41], off nt
	v_mad_i64_i32 v[40:41], s[2:3], v39, s29, v[68:69]
	v_mad_i64_i32 v[38:39], s[2:3], v38, s29, v[68:69]
	global_load_dword v40, v[40:41], off nt
	s_nop 0
	global_load_dword v41, v[38:39], off nt
	v_mad_i64_i32 v[38:39], s[2:3], v37, s29, v[68:69]
	v_mad_i64_i32 v[36:37], s[2:3], v36, s29, v[68:69]
	global_load_dword v38, v[38:39], off nt
	s_nop 0
	global_load_dword v39, v[36:37], off nt
	v_mad_i64_i32 v[36:37], s[2:3], v35, s29, v[68:69]
	global_load_dword v35, v[36:37], off nt
	s_waitcnt vmcnt(0)
	ds_write2_b32 v71, v86, v66 offset1:66
	ds_write2_b32 v71, v67, v64 offset0:132 offset1:198
	ds_write2_b32 v72, v65, v62 offset0:8 offset1:74
	ds_write2_b32 v72, v63, v60 offset0:140 offset1:206
	ds_write2_b32 v80, v61, v58 offset0:16 offset1:82
	ds_write2_b32 v80, v59, v56 offset0:148 offset1:214
	ds_write2_b32 v82, v57, v54 offset0:24 offset1:90
	ds_write2_b32 v82, v55, v52 offset0:156 offset1:222
	ds_write2_b32 v83, v53, v50 offset0:32 offset1:98
	ds_write2_b32 v83, v51, v48 offset0:164 offset1:230
	ds_write2_b32 v84, v49, v46 offset0:40 offset1:106
	ds_write2_b32 v84, v47, v44 offset0:172 offset1:238
	ds_write2_b32 v85, v45, v42 offset0:48 offset1:114
	ds_write2_b32 v85, v43, v40 offset0:180 offset1:246
	ds_write2_b32 v34, v41, v38 offset0:56 offset1:122
	ds_write2_b32 v34, v39, v35 offset0:188 offset1:254
	s_waitcnt lgkmcnt(0)
	ds_read2_b32 v[40:41], v76 offset0:33 offset1:41
	ds_read2_b32 v[42:43], v76 offset1:8
	ds_read2_b32 v[44:45], v76 offset0:66 offset1:74
	ds_read2_b32 v[46:47], v76 offset0:99 offset1:107
	ds_read2_b32 v[48:49], v76 offset0:132 offset1:140
	ds_read2_b32 v[50:51], v76 offset0:165 offset1:173
	ds_read2_b32 v[52:53], v76 offset0:198 offset1:206
	ds_read2_b32 v[54:55], v76 offset0:231 offset1:239
	v_add_u32_e32 v56, s0, v75
	v_ashrrev_i32_e32 v57, 31, v56
	v_lshl_add_u64 v[38:39], s[4:5], 1, v[16:17]
	v_lshlrev_b64 v[56:57], 11, v[56:57]
	s_waitcnt lgkmcnt(6)
	v_cvt_pk_bf16_f32 v34, v42, v40
	s_waitcnt lgkmcnt(4)
	v_cvt_pk_bf16_f32 v35, v44, v46
	s_waitcnt lgkmcnt(2)
	v_cvt_pk_bf16_f32 v36, v48, v50
	s_waitcnt lgkmcnt(0)
	v_cvt_pk_bf16_f32 v37, v52, v54
	v_lshl_add_u64 v[56:57], v[38:39], 0, v[56:57]
	v_add_u32_e32 v40, s0, v77
	global_store_dwordx4 v[56:57], v[34:37], off nt
	v_add_u32_e32 v56, s0, v78
	v_ashrrev_i32_e32 v57, 31, v56
	v_cvt_pk_bf16_f32 v34, v43, v41
	v_ashrrev_i32_e32 v41, 31, v40
	v_lshlrev_b64 v[40:41], 11, v[40:41]
	v_cvt_pk_bf16_f32 v35, v45, v47
	v_cvt_pk_bf16_f32 v36, v49, v51
	v_cvt_pk_bf16_f32 v37, v53, v55
	v_lshl_add_u64 v[40:41], v[38:39], 0, v[40:41]
	global_store_dwordx4 v[40:41], v[34:37], off nt
	ds_read2_b32 v[40:41], v76 offset0:49 offset1:57
	ds_read2_b32 v[42:43], v76 offset0:16 offset1:24
	ds_read2_b32 v[44:45], v76 offset0:82 offset1:90
	ds_read2_b32 v[46:47], v76 offset0:115 offset1:123
	ds_read2_b32 v[48:49], v76 offset0:148 offset1:156
	ds_read2_b32 v[50:51], v76 offset0:181 offset1:189
	ds_read2_b32 v[52:53], v76 offset0:214 offset1:222
	ds_read2_b32 v[54:55], v76 offset0:247 offset1:255
	v_lshlrev_b64 v[56:57], 11, v[56:57]
	s_waitcnt lgkmcnt(6)
	v_cvt_pk_bf16_f32 v34, v42, v40
	s_waitcnt lgkmcnt(4)
	v_cvt_pk_bf16_f32 v35, v44, v46
	s_waitcnt lgkmcnt(2)
	v_cvt_pk_bf16_f32 v36, v48, v50
	s_waitcnt lgkmcnt(0)
	v_cvt_pk_bf16_f32 v37, v52, v54
	v_lshl_add_u64 v[56:57], v[38:39], 0, v[56:57]
	v_add_u32_e32 v40, s0, v79
	global_store_dwordx4 v[56:57], v[34:37], off nt
	s_nop 1
	v_cvt_pk_bf16_f32 v34, v43, v41
	v_ashrrev_i32_e32 v41, 31, v40
	v_lshlrev_b64 v[40:41], 11, v[40:41]
	v_cvt_pk_bf16_f32 v35, v45, v47
	v_cvt_pk_bf16_f32 v36, v49, v51
	v_cvt_pk_bf16_f32 v37, v53, v55
	v_lshl_add_u64 v[38:39], v[38:39], 0, v[40:41]
	global_store_dwordx4 v[38:39], v[34:37], off nt
	s_waitcnt lgkmcnt(0)
	s_branch .LBB0_412

; __device__ __forceinline__ u32x4 pack8(f32x4 a, f32x4 b) { u32x4 w; w.x = cvt_pk(a[0], a[1]); w.y = cvt_pk(a[2], a[3]); w.z = cvt_pk(b[0], b[1]); w.w = cvt_pk(b[2], b[3]); return w; }
; template <int PART>
; __device__ __forceinline__ void phase0(const Ptrs& P, LAS float* scr, int gw, int NGW, int lane) {
;     ...
;     if (PART == 1) { bf16_t* PB = (bf16_t*)(ws + WS_PB); const int ngrp = MT * PLE / 8;
; #pragma unroll 4
;         for (int gidx = gw * 64 + lane; gidx < ngrp; gidx += NGW * 64) { const f32x4 a = *(const f32x4*)(P.p + (size_t)gidx * 8), b = *(const f32x4*)(P.p + (size_t)gidx * 8 + 4); *(u32x4*)(PB + (size_t)gidx * 8) = pack8(a, b); } }
.LBB0_451:
	global_load_dwordx4 v[8:11], v[4:5], off offset:-16 nt
	global_load_dwordx4 v[12:15], v[4:5], off nt
	v_add_u32_e32 v7, -1, v7
	v_cmp_eq_u32_e64 s[0:1], 0, v7
	v_add_u32_e32 v0, s62, v0
	v_lshl_add_u64 v[4:5], v[4:5], 0, s[44:45]
	s_or_b64 s[36:37], s[0:1], s[36:37]
	s_waitcnt vmcnt(0)
	v_cvt_pk_bf16_f32 v8, v8, v9
	v_cvt_pk_bf16_f32 v9, v10, v11
	v_cvt_pk_bf16_f32 v10, v12, v13
	v_cvt_pk_bf16_f32 v11, v14, v15
	global_store_dwordx4 v[2:3], v[8:11], off nt
	v_lshl_add_u64 v[2:3], v[2:3], 0, s[2:3]
	s_andn2_b64 exec, exec, s[36:37]
	s_cbranch_execnz .LBB0_451
	s_or_b64 exec, exec, s[36:37]

; __device__ __forceinline__ u32x4 pack8(f32x4 a, f32x4 b) { u32x4 w; w.x = cvt_pk(a[0], a[1]); w.y = cvt_pk(a[2], a[3]); w.z = cvt_pk(b[0], b[1]); w.w = cvt_pk(b[2], b[3]); return w; }
; template <int PART>
; __device__ __forceinline__ void phase0(const Ptrs& P, LAS float* scr, int gw, int NGW, int lane) {
;     ...
;     if (PART == 1) { bf16_t* PB = (bf16_t*)(ws + WS_PB); const int ngrp = MT * PLE / 8;
; #pragma unroll 4
;         for (int gidx = gw * 64 + lane; gidx < ngrp; gidx += NGW * 64) { const f32x4 a = *(const f32x4*)(P.p + (size_t)gidx * 8), b = *(const f32x4*)(P.p + (size_t)gidx * 8 + 4); *(u32x4*)(PB + (size_t)gidx * 8) = pack8(a, b); } }
.LBB0_455:
	v_ashrrev_i32_e32 v1, 31, v0
	v_lshlrev_b64 v[2:3], 5, v[0:1]
	v_lshl_add_u64 v[6:7], s[78:79], 0, v[2:3]
	global_load_dwordx4 v[2:5], v[6:7], off offset:16 nt
	s_nop 0
	global_load_dwordx4 v[6:9], v[6:7], off nt
	v_add_u32_e32 v10, s62, v0
	v_ashrrev_i32_e32 v11, 31, v10
	v_add_u32_e32 v12, s8, v0
	v_ashrrev_i32_e32 v13, 31, v12
	s_mul_i32 s2, s6, 0x600
	s_waitcnt vmcnt(0)
	v_cvt_pk_bf16_f32 v6, v6, v7
	v_cvt_pk_bf16_f32 v7, v8, v9
	v_cvt_pk_bf16_f32 v8, v2, v3
	v_cvt_pk_bf16_f32 v9, v4, v5
	v_lshl_add_u64 v[2:3], v[0:1], 4, s[60:61]
	global_store_dwordx4 v[2:3], v[6:9], off nt
	v_lshlrev_b64 v[2:3], 5, v[10:11]
	s_nop 0
	v_lshl_add_u64 v[6:7], s[78:79], 0, v[2:3]
	global_load_dwordx4 v[2:5], v[6:7], off offset:16 nt
	s_nop 0
	global_load_dwordx4 v[6:9], v[6:7], off nt
	s_waitcnt vmcnt(0)
	v_cvt_pk_bf16_f32 v6, v6, v7
	v_cvt_pk_bf16_f32 v7, v8, v9
	v_cvt_pk_bf16_f32 v8, v2, v3
	v_cvt_pk_bf16_f32 v9, v4, v5
	v_lshl_add_u64 v[2:3], v[10:11], 4, s[60:61]
	global_store_dwordx4 v[2:3], v[6:9], off nt
	v_lshlrev_b64 v[2:3], 5, v[12:13]
	s_nop 0
	v_lshl_add_u64 v[6:7], s[78:79], 0, v[2:3]
	global_load_dwordx4 v[2:5], v[6:7], off offset:16 nt
	s_nop 0
	global_load_dwordx4 v[6:9], v[6:7], off nt
	s_waitcnt vmcnt(0)
	v_cvt_pk_bf16_f32 v6, v6, v7
	v_cvt_pk_bf16_f32 v7, v8, v9
	v_cvt_pk_bf16_f32 v8, v2, v3
	v_cvt_pk_bf16_f32 v9, v4, v5
	v_lshl_add_u64 v[2:3], v[12:13], 4, s[60:61]
	global_store_dwordx4 v[2:3], v[6:9], off nt
	s_nop 1
	v_add_u32_e32 v8, s2, v0
	v_ashrrev_i32_e32 v9, 31, v8
	v_lshlrev_b64 v[0:1], 5, v[8:9]
	v_lshl_add_u64 v[4:5], s[78:79], 0, v[0:1]
	global_load_dwordx4 v[0:3], v[4:5], off offset:16 nt
	s_nop 0
	global_load_dwordx4 v[4:7], v[4:5], off nt
	s_add_i32 s2, s62, s62
	s_add_i32 s2, s2, s62
	s_waitcnt vmcnt(0)
	v_cvt_pk_bf16_f32 v4, v4, v5
	v_cvt_pk_bf16_f32 v5, v6, v7
	v_cvt_pk_bf16_f32 v6, v0, v1
	v_cvt_pk_bf16_f32 v7, v2, v3
	v_lshl_add_u64 v[0:1], v[8:9], 4, s[60:61]
	global_store_dwordx4 v[0:1], v[4:7], off nt
	v_add_u32_e32 v0, s2, v10
	s_mov_b32 s2, 0x7ffff
	v_cmp_lt_i32_e32 vcc, s2, v0
	s_or_b64 s[0:1], vcc, s[0:1]
	s_andn2_b64 exec, exec, s[0:1]
	s_cbranch_execnz .LBB0_455
